# all four gemm256 K-loops: LDS-DMA issue spread over first K-half + A-fragment pairs read one MFMA group ahead
# speedup vs baseline: 1.0233x; 1.0094x over previous
; #define GLDS_STAGE(st, kt_) do { \
;         _Pragma("unroll") for (int i_ = 0; i_ < FI; ++i_) { \
;             glds16(ap + (size_t)(32 * i_) * lda + (kt_) * 64, l3a + (st) + tid * 16 + i_ * 4096); \
;             glds16(bp + (size_t)(32 * i_) * ldb + (kt_) * 64, l3a + (st) + OPB + tid * 16 + i_ * 4096); } } while (0)
; #define GLDS_STAGE(st, kt_) do { \
;         _Pragma("unroll") for (int i_ = 0; i_ < 4; ++i_) { \
;             glds16(ap + (size_t)(64 * i_) * lda + (kt_) * 64, l3a + (st) + tid * 16 + i_ * 8192); \
;             glds16(bp + (size_t)(64 * i_) * ldb + (kt_) * 64, l3a + (st) + 32768 + tid * 16 + i_ * 8192); } } while (0)
; template <class Epi>
; DEV void gemm256_tile(const bf16_t* __restrict__ A, int lda, const bf16_t* __restrict__ Bt, int ldb, int K, unsigned char* lds, const Epi& epi) {
;     ...
;     for (int kt = 0; kt < nk; ++kt) {
;         const int cur = (kt & 1) * 65536;
;         asm volatile("s_waitcnt vmcnt(0)" ::: "memory");
;         __syncthreads();
;         if (kt + 1 < nk) GLDS_STAGE(cur ^ 65536, kt + 1);
; #pragma unroll
;         for (int kh = 0; kh < 2; ++kh) {
;             bf16x8 bfr[4];
;             const int ch = ((kh * 4 + fq) ^ sw) << 4;
; #pragma unroll
;             for (int i = 0; i < 4; ++i) bfr[i] = *(const bf16x8*)(lds + cur + boff + i * 2048 + ch);
; #pragma unroll
;             for (int mh = 0; mh < 2; ++mh) {
;                 bf16x8 af[4];
; #pragma unroll
;                 for (int i = 0; i < 4; ++i) af[i] = *(const bf16x8*)(lds + cur + aoff + (mh * 4 + i) * 2048 + ch);
; #pragma unroll
;                 for (int mi = 0; mi < 4; ++mi)
; #pragma unroll
;                     for (int ni = 0; ni < 4; ++ni) acc[mh * 4 + mi][ni] = __builtin_amdgcn_mfma_f32_16x16x32_bf16(bfr[ni], af[mi], acc[mh * 4 + mi][ni], 0, 0, 0);
;             }
;         }
.LBB0_174:
	s_and_b32 s48, s21, 0x10000
	s_xor_b32 s49, s48, 0x10000
	v_add_u32_e32 v216, s49, v142
	v_add_u32_e32 v217, s49, v156
	s_waitcnt vmcnt(0) lgkmcnt(0)
	s_barrier
	v_or_b32_e32 v248, s48, v175
	v_add_u32_e32 v249, s48, v157
	v_add_u32_e32 v244, v248, v174
	v_add_u32_e32 v245, v249, v174
	ds_read_b128 v[176:179], v244 offset:32768
	ds_read_b128 v[180:183], v244 offset:34816
	ds_read_b128 v[184:187], v244 offset:36864
	ds_read_b128 v[188:191], v244 offset:38912
	ds_read_b128 v[228:231], v245
	ds_read_b128 v[232:235], v245 offset:2048
	ds_read_b128 v[236:239], v245 offset:4096
	ds_read_b128 v[240:243], v245 offset:6144
	v_readfirstlane_b32 s40, v216
	v_readfirstlane_b32 s44, v217
	v_add_u32_e32 v246, v248, v155
	v_add_u32_e32 v247, v249, v155
	s_mov_b32 m0, s40
	v_lshl_add_u64 v[204:205], v[144:145], 0, s[4:5]
	global_load_lds_dwordx4 v[144:145], off
	s_mov_b32 m0, s44
	v_lshl_add_u64 v[210:211], v[146:147], 0, s[4:5]
	global_load_lds_dwordx4 v[146:147], off
	s_add_i32 s41, s40, 0x2000
	s_add_i32 s45, s44, 0x2000
	s_add_i32 s42, s40, 0x4000
	s_add_i32 s46, s44, 0x4000
	s_add_i32 s43, s40, 0x6000
	s_add_i32 s47, s44, 0x6000
	s_add_i32 s21, s21, 0x10000
	s_waitcnt lgkmcnt(3)
	v_mfma_f32_16x16x32_bf16 v[126:129], v[176:179], v[228:231], v[126:129]
	v_lshl_add_u64 v[206:207], v[144:145], 0, s[6:7]
	v_mfma_f32_16x16x32_bf16 v[122:125], v[180:183], v[228:231], v[122:125]
	v_lshl_add_u64 v[212:213], v[146:147], 0, s[6:7]
	v_mfma_f32_16x16x32_bf16 v[118:121], v[184:187], v[228:231], v[118:121]
	v_lshl_add_u64 v[208:209], v[144:145], 0, s[8:9]
	v_mfma_f32_16x16x32_bf16 v[114:117], v[188:191], v[228:231], v[114:117]
	v_lshl_add_u64 v[214:215], v[146:147], 0, s[8:9]
	s_waitcnt lgkmcnt(2)
	v_mfma_f32_16x16x32_bf16 v[110:113], v[176:179], v[232:235], v[110:113]
	v_mfma_f32_16x16x32_bf16 v[106:109], v[180:183], v[232:235], v[106:109]
	v_mfma_f32_16x16x32_bf16 v[102:105], v[184:187], v[232:235], v[102:105]
	v_mfma_f32_16x16x32_bf16 v[98:101], v[188:191], v[232:235], v[98:101]
	s_waitcnt lgkmcnt(1)
	v_mfma_f32_16x16x32_bf16 v[94:97], v[176:179], v[236:239], v[94:97]
	ds_read_b128 v[228:231], v245 offset:8192
	v_mfma_f32_16x16x32_bf16 v[90:93], v[180:183], v[236:239], v[90:93]
	ds_read_b128 v[232:235], v245 offset:10240
	v_mfma_f32_16x16x32_bf16 v[86:89], v[184:187], v[236:239], v[86:89]
	s_mov_b32 m0, s41
	v_mfma_f32_16x16x32_bf16 v[82:85], v[188:191], v[236:239], v[82:85]
	global_load_lds_dwordx4 v[204:205], off
	s_waitcnt lgkmcnt(2)
	v_mfma_f32_16x16x32_bf16 v[78:81], v[176:179], v[240:243], v[78:81]
	s_mov_b32 m0, s45
	v_mfma_f32_16x16x32_bf16 v[74:77], v[180:183], v[240:243], v[74:77]
	global_load_lds_dwordx4 v[210:211], off
	v_mfma_f32_16x16x32_bf16 v[70:73], v[184:187], v[240:243], v[70:73]
	v_mfma_f32_16x16x32_bf16 v[66:69], v[188:191], v[240:243], v[66:69]
	s_waitcnt lgkmcnt(1)
	v_mfma_f32_16x16x32_bf16 v[62:65], v[176:179], v[228:231], v[62:65]
	ds_read_b128 v[236:239], v245 offset:12288
	v_mfma_f32_16x16x32_bf16 v[58:61], v[180:183], v[228:231], v[58:61]
	ds_read_b128 v[240:243], v245 offset:14336
	v_mfma_f32_16x16x32_bf16 v[54:57], v[184:187], v[228:231], v[54:57]
	s_mov_b32 m0, s42
	v_mfma_f32_16x16x32_bf16 v[50:53], v[188:191], v[228:231], v[50:53]
	global_load_lds_dwordx4 v[206:207], off
	s_waitcnt lgkmcnt(2)
	v_mfma_f32_16x16x32_bf16 v[46:49], v[176:179], v[232:235], v[46:49]
	s_mov_b32 m0, s46
	v_mfma_f32_16x16x32_bf16 v[42:45], v[180:183], v[232:235], v[42:45]
	global_load_lds_dwordx4 v[212:213], off
	v_mfma_f32_16x16x32_bf16 v[34:37], v[184:187], v[232:235], v[34:37]
	v_mfma_f32_16x16x32_bf16 v[30:33], v[188:191], v[232:235], v[30:33]
	s_waitcnt lgkmcnt(1)
	v_mfma_f32_16x16x32_bf16 v[26:29], v[176:179], v[236:239], v[26:29]
	ds_read_b128 v[192:195], v246 offset:32768
	v_mfma_f32_16x16x32_bf16 v[22:25], v[180:183], v[236:239], v[22:25]
	ds_read_b128 v[196:199], v246 offset:34816
	v_mfma_f32_16x16x32_bf16 v[18:21], v[184:187], v[236:239], v[18:21]
	ds_read_b128 v[220:223], v246 offset:36864
	v_mfma_f32_16x16x32_bf16 v[14:17], v[188:191], v[236:239], v[14:17]
	ds_read_b128 v[224:227], v246 offset:38912
	s_waitcnt lgkmcnt(4)
	v_mfma_f32_16x16x32_bf16 v[10:13], v[176:179], v[240:243], v[10:13]
	ds_read_b128 v[228:231], v247
	v_mfma_f32_16x16x32_bf16 v[6:9], v[180:183], v[240:243], v[6:9]
	ds_read_b128 v[232:235], v247 offset:2048
	v_mfma_f32_16x16x32_bf16 v[2:5], v[184:187], v[240:243], v[2:5]
	s_mov_b32 m0, s43
	v_mfma_f32_16x16x32_bf16 v[38:41], v[188:191], v[240:243], v[38:41]
	global_load_lds_dwordx4 v[208:209], off
	s_mov_b32 m0, s47
	v_lshl_add_u64 v[144:145], v[144:145], 0, s[10:11]
	global_load_lds_dwordx4 v[214:215], off
	v_lshl_add_u64 v[146:147], v[146:147], 0, s[10:11]
	s_waitcnt lgkmcnt(1)
	v_mfma_f32_16x16x32_bf16 v[126:129], v[192:195], v[228:231], v[126:129]
	ds_read_b128 v[236:239], v247 offset:4096
	v_mfma_f32_16x16x32_bf16 v[122:125], v[196:199], v[228:231], v[122:125]
	ds_read_b128 v[240:243], v247 offset:6144
	v_mfma_f32_16x16x32_bf16 v[118:121], v[220:223], v[228:231], v[118:121]
	v_mfma_f32_16x16x32_bf16 v[114:117], v[224:227], v[228:231], v[114:117]
	s_waitcnt lgkmcnt(2)
	v_mfma_f32_16x16x32_bf16 v[110:113], v[192:195], v[232:235], v[110:113]
	v_mfma_f32_16x16x32_bf16 v[106:109], v[196:199], v[232:235], v[106:109]
	v_mfma_f32_16x16x32_bf16 v[102:105], v[220:223], v[232:235], v[102:105]
	v_mfma_f32_16x16x32_bf16 v[98:101], v[224:227], v[232:235], v[98:101]
	s_waitcnt lgkmcnt(1)
	v_mfma_f32_16x16x32_bf16 v[94:97], v[192:195], v[236:239], v[94:97]
	ds_read_b128 v[228:231], v247 offset:8192
	v_mfma_f32_16x16x32_bf16 v[90:93], v[196:199], v[236:239], v[90:93]
	ds_read_b128 v[232:235], v247 offset:10240
	v_mfma_f32_16x16x32_bf16 v[86:89], v[220:223], v[236:239], v[86:89]
	v_mfma_f32_16x16x32_bf16 v[82:85], v[224:227], v[236:239], v[82:85]
	s_waitcnt lgkmcnt(2)
; DEV unsigned cvt_pk_bf16(float lo, float hi) { const f32x2_t v = {lo, hi}; const bf16x2_t b = __builtin_convertvector(v, bf16x2_t); return __builtin_bit_cast(unsigned, b); }
; template <class Epi>
; DEV void gemm256_tile(const bf16_t* __restrict__ A, int lda, const bf16_t* __restrict__ Bt, int ldb, int K, unsigned char* lds, const Epi& epi) {
;     ...
;         for (int kh = 0; kh < 2; ++kh) {
;             bf16x8 bfr[4];
;             const int ch = ((kh * 4 + fq) ^ sw) << 4;
; #pragma unroll
;             for (int i = 0; i < 4; ++i) bfr[i] = *(const bf16x8*)(lds + cur + boff + i * 2048 + ch);
; #pragma unroll
;             for (int mh = 0; mh < 2; ++mh) {
;                 bf16x8 af[4];
; #pragma unroll
;                 for (int i = 0; i < 4; ++i) af[i] = *(const bf16x8*)(lds + cur + aoff + (mh * 4 + i) * 2048 + ch);
; #pragma unroll
;                 for (int mi = 0; mi < 4; ++mi)
; #pragma unroll
;                     for (int ni = 0; ni < 4; ++ni) acc[mh * 4 + mi][ni] = __builtin_amdgcn_mfma_f32_16x16x32_bf16(bfr[ni], af[mi], acc[mh * 4 + mi][ni], 0, 0, 0);
;             }
;         }
;     }
;     ...
;     __syncthreads();
;     if constexpr (Epi::STAGE) {
; #pragma unroll
;         for (int mi = 0; mi < 8; ++mi)
; #pragma unroll
;             for (int ni = 0; ni < 4; ++ni) {
;                 const int row = wr * 128 + mi * 16 + fr, col = wc * 64 + ni * 16 + fq * 4;
;                 const f32x4 v = epi.xform(row, col, acc[mi][ni]);
;                 uint2 w; w.x = cvt_pk_bf16(v[0], v[1]); w.y = cvt_pk_bf16(v[2], v[3]);
;                 *(uint2*)(lds + row * 512 + ((((col >> 3) ^ (row & 31)) << 4) | (((col >> 2) & 1) << 3))) = w;
	v_mfma_f32_16x16x32_bf16 v[78:81], v[192:195], v[240:243], v[78:81]
	v_mfma_f32_16x16x32_bf16 v[74:77], v[196:199], v[240:243], v[74:77]
	v_mfma_f32_16x16x32_bf16 v[70:73], v[220:223], v[240:243], v[70:73]
	v_mfma_f32_16x16x32_bf16 v[66:69], v[224:227], v[240:243], v[66:69]
	s_waitcnt lgkmcnt(1)
	v_mfma_f32_16x16x32_bf16 v[62:65], v[192:195], v[228:231], v[62:65]
	ds_read_b128 v[236:239], v247 offset:12288
	v_mfma_f32_16x16x32_bf16 v[58:61], v[196:199], v[228:231], v[58:61]
	ds_read_b128 v[240:243], v247 offset:14336
	v_mfma_f32_16x16x32_bf16 v[54:57], v[220:223], v[228:231], v[54:57]
	v_mfma_f32_16x16x32_bf16 v[50:53], v[224:227], v[228:231], v[50:53]
	s_waitcnt lgkmcnt(2)
	v_mfma_f32_16x16x32_bf16 v[46:49], v[192:195], v[232:235], v[46:49]
	v_mfma_f32_16x16x32_bf16 v[42:45], v[196:199], v[232:235], v[42:45]
	v_mfma_f32_16x16x32_bf16 v[34:37], v[220:223], v[232:235], v[34:37]
	v_mfma_f32_16x16x32_bf16 v[30:33], v[224:227], v[232:235], v[30:33]
	s_waitcnt lgkmcnt(1)
	v_mfma_f32_16x16x32_bf16 v[26:29], v[192:195], v[236:239], v[26:29]
	v_mfma_f32_16x16x32_bf16 v[22:25], v[196:199], v[236:239], v[22:25]
	v_mfma_f32_16x16x32_bf16 v[18:21], v[220:223], v[236:239], v[18:21]
	v_mfma_f32_16x16x32_bf16 v[14:17], v[224:227], v[236:239], v[14:17]
	s_waitcnt lgkmcnt(0)
	v_mfma_f32_16x16x32_bf16 v[10:13], v[192:195], v[240:243], v[10:13]
	v_mfma_f32_16x16x32_bf16 v[6:9], v[196:199], v[240:243], v[6:9]
	v_mfma_f32_16x16x32_bf16 v[2:5], v[220:223], v[240:243], v[2:5]
	v_mfma_f32_16x16x32_bf16 v[38:41], v[224:227], v[240:243], v[38:41]
	s_cmp_eq_u32 s21, 0x1f0000
	s_cbranch_scc0 .LBB0_174
	v_or_b32_e32 v156, 0x18000, v175
	v_add_u32_e32 v157, 0x10000, v157
	v_add_u32_e32 v186, v156, v174
	v_add_u32_e32 v194, v157, v174
	s_waitcnt vmcnt(0)
	s_barrier
	ds_read_b128 v[144:147], v186
	ds_read_b128 v[178:181], v186 offset:2048
	ds_read_b128 v[174:177], v194
	ds_read_b128 v[182:185], v186 offset:4096
	ds_read_b128 v[186:189], v186 offset:6144
	s_waitcnt lgkmcnt(2)
	v_mfma_f32_16x16x32_bf16 v[126:129], v[144:147], v[174:177], v[126:129]
	s_sext_i32_i16 s20, s20
	s_lshl_b32 s20, s20, 8
	s_ashr_i32 s21, s20, 31
	v_mfma_f32_16x16x32_bf16 v[122:125], v[178:181], v[174:177], v[122:125]
	s_waitcnt lgkmcnt(1)
	v_mfma_f32_16x16x32_bf16 v[118:121], v[182:185], v[174:177], v[118:121]
	s_waitcnt lgkmcnt(0)
	v_mfma_f32_16x16x32_bf16 v[114:117], v[186:189], v[174:177], v[114:117]
	ds_read_b128 v[174:177], v194 offset:2048
	s_waitcnt lgkmcnt(0)
	v_mfma_f32_16x16x32_bf16 v[110:113], v[144:147], v[174:177], v[110:113]
	v_mfma_f32_16x16x32_bf16 v[106:109], v[178:181], v[174:177], v[106:109]
	v_mfma_f32_16x16x32_bf16 v[102:105], v[182:185], v[174:177], v[102:105]
	v_mfma_f32_16x16x32_bf16 v[98:101], v[186:189], v[174:177], v[98:101]
	ds_read_b128 v[174:177], v194 offset:4096
	s_waitcnt lgkmcnt(0)
	v_mfma_f32_16x16x32_bf16 v[94:97], v[144:147], v[174:177], v[94:97]
	v_mfma_f32_16x16x32_bf16 v[90:93], v[178:181], v[174:177], v[90:93]
	v_mfma_f32_16x16x32_bf16 v[86:89], v[182:185], v[174:177], v[86:89]
	v_mfma_f32_16x16x32_bf16 v[82:85], v[186:189], v[174:177], v[82:85]
	ds_read_b128 v[174:177], v194 offset:6144
	s_waitcnt lgkmcnt(0)
	v_mfma_f32_16x16x32_bf16 v[78:81], v[144:147], v[174:177], v[78:81]
	v_mfma_f32_16x16x32_bf16 v[74:77], v[178:181], v[174:177], v[74:77]
	v_mfma_f32_16x16x32_bf16 v[70:73], v[182:185], v[174:177], v[70:73]
	v_mfma_f32_16x16x32_bf16 v[66:69], v[186:189], v[174:177], v[66:69]
	ds_read_b128 v[174:177], v194 offset:8192
	ds_read_b128 v[190:193], v194 offset:10240
	s_waitcnt lgkmcnt(1)
	v_mfma_f32_16x16x32_bf16 v[62:65], v[144:147], v[174:177], v[62:65]
	v_mfma_f32_16x16x32_bf16 v[58:61], v[178:181], v[174:177], v[58:61]
	v_mfma_f32_16x16x32_bf16 v[54:57], v[182:185], v[174:177], v[54:57]
	v_mfma_f32_16x16x32_bf16 v[50:53], v[186:189], v[174:177], v[50:53]
	ds_read_b128 v[174:177], v194 offset:12288
	s_waitcnt lgkmcnt(1)
	v_mfma_f32_16x16x32_bf16 v[46:49], v[144:147], v[190:193], v[46:49]
	v_mfma_f32_16x16x32_bf16 v[42:45], v[178:181], v[190:193], v[42:45]
	v_mfma_f32_16x16x32_bf16 v[34:37], v[182:185], v[190:193], v[34:37]
	v_mfma_f32_16x16x32_bf16 v[30:33], v[186:189], v[190:193], v[30:33]
	ds_read_b128 v[190:193], v194 offset:14336
	s_waitcnt lgkmcnt(1)
	v_mfma_f32_16x16x32_bf16 v[194:197], v[144:147], v[174:177], v[26:29]
	s_nop 2
	v_add_u32_e32 v29, v156, v155
	ds_read_b128 v[198:201], v29
	ds_read_b128 v[202:205], v29 offset:2048
	ds_read_b128 v[206:209], v29 offset:4096
	ds_read_b128 v[210:213], v29 offset:6144
	v_add_u32_e32 v29, v157, v155
	v_mfma_f32_16x16x32_bf16 v[22:25], v[178:181], v[174:177], v[22:25]
	v_and_b32_e32 v28, 0xc0, v150
	v_lshl_or_b32 v153, v153, 2, v28
	v_lshlrev_b32_e32 v28, 3, v152
	v_mfma_f32_16x16x32_bf16 v[18:21], v[182:185], v[174:177], v[18:21]
	v_mad_i64_i32 v[26:27], s[22:23], s19, v149, v[172:173]
	v_lshl_add_u64 v[26:27], s[20:21], 1, v[26:27]
	v_mfma_f32_16x16x32_bf16 v[14:17], v[186:189], v[174:177], v[14:17]
	ds_read_b128 v[174:177], v29
	ds_read_b128 v[214:217], v29 offset:2048
	ds_read_b128 v[218:221], v29 offset:4096
	ds_read_b128 v[222:225], v29 offset:6144
	s_mov_b32 s19, 0
	s_waitcnt lgkmcnt(3)
	v_mfma_f32_16x16x32_bf16 v[126:129], v[198:201], v[174:177], v[126:129]
	v_mfma_f32_16x16x32_bf16 v[122:125], v[202:205], v[174:177], v[122:125]
	s_waitcnt lgkmcnt(1)
	v_mfma_f32_16x16x32_bf16 v[94:97], v[198:201], v[218:221], v[94:97]
	v_mfma_f32_16x16x32_bf16 v[10:13], v[144:147], v[190:193], v[10:13]
	ds_read_b128 v[144:147], v29 offset:8192
	ds_read_b128 v[226:229], v29 offset:10240
	ds_read_b128 v[230:233], v29 offset:12288
	ds_read_b128 v[234:237], v29 offset:14336
	v_lshlrev_b32_e32 v29, 9, v154
	v_and_or_b32 v152, v28, 8, v29
	v_mfma_f32_16x16x32_bf16 v[118:121], v[206:209], v[174:177], v[118:121]
	v_cvt_pk_bf16_f32 v28, v126, v127
	v_lshrrev_b32_e32 v126, 3, v153
	v_xor_b32_e32 v127, v126, v151
	v_mfma_f32_16x16x32_bf16 v[90:93], v[202:205], v[218:221], v[90:93]
	v_cvt_pk_bf16_f32 v29, v128, v129
	v_lshl_or_b32 v127, v127, 4, v152
	v_cvt_pk_bf16_f32 v122, v122, v123
	v_mfma_f32_16x16x32_bf16 v[114:117], v[210:213], v[174:177], v[114:117]
	v_cvt_pk_bf16_f32 v123, v124, v125
	v_bitop3_b32 v124, v126, v151, 2 bitop3:0x36
	v_cvt_pk_bf16_f32 v94, v94, v95
	v_mfma_f32_16x16x32_bf16 v[86:89], v[206:209], v[218:221], v[86:89]
	v_cvt_pk_bf16_f32 v95, v96, v97
	s_waitcnt lgkmcnt(0)
	s_barrier
; DEV unsigned cvt_pk_bf16(float lo, float hi) { const f32x2_t v = {lo, hi}; const bf16x2_t b = __builtin_convertvector(v, bf16x2_t); return __builtin_bit_cast(unsigned, b); }
; template <class Epi>
; DEV void gemm256_tile(const bf16_t* __restrict__ A, int lda, const bf16_t* __restrict__ Bt, int ldb, int K, unsigned char* lds, const Epi& epi) {
;     ...
;                 for (int mi = 0; mi < 4; ++mi)
; #pragma unroll
;                     for (int ni = 0; ni < 4; ++ni) acc[mh * 4 + mi][ni] = __builtin_amdgcn_mfma_f32_16x16x32_bf16(bfr[ni], af[mi], acc[mh * 4 + mi][ni], 0, 0, 0);
;             }
;         }
;     }
;     ...
;     __syncthreads();
;     if constexpr (Epi::STAGE) {
; #pragma unroll
;         for (int mi = 0; mi < 8; ++mi)
; #pragma unroll
;             for (int ni = 0; ni < 4; ++ni) {
;                 const int row = wr * 128 + mi * 16 + fr, col = wc * 64 + ni * 16 + fq * 4;
;                 const f32x4 v = epi.xform(row, col, acc[mi][ni]);
;                 uint2 w; w.x = cvt_pk_bf16(v[0], v[1]); w.y = cvt_pk_bf16(v[2], v[3]);
;                 *(uint2*)(lds + row * 512 + ((((col >> 3) ^ (row & 31)) << 4) | (((col >> 2) & 1) << 3))) = w;
;             }
;         __syncthreads();
	v_mfma_f32_16x16x32_bf16 v[110:113], v[198:201], v[214:217], v[110:113]
	v_lshl_add_u32 v124, v124, 4, v152
	v_cvt_pk_bf16_f32 v118, v118, v119
	v_mfma_f32_16x16x32_bf16 v[82:85], v[210:213], v[218:221], v[82:85]
	v_cvt_pk_bf16_f32 v119, v120, v121
	v_bitop3_b32 v120, v126, v151, 4 bitop3:0x36
	ds_write2st64_b64 v127, v[28:29], v[94:95] offset1:32
	v_mfma_f32_16x16x32_bf16 v[106:109], v[202:205], v[214:217], v[106:109]
	v_cvt_pk_bf16_f32 v28, v90, v91
	v_cvt_pk_bf16_f32 v29, v92, v93
	v_lshl_add_u32 v120, v120, 4, v152
	v_mfma_f32_16x16x32_bf16 v[78:81], v[198:201], v[222:225], v[78:81]
	v_cvt_pk_bf16_f32 v114, v114, v115
	v_cvt_pk_bf16_f32 v115, v116, v117
	v_bitop3_b32 v116, v126, v151, 6 bitop3:0x36
	v_mfma_f32_16x16x32_bf16 v[102:105], v[206:209], v[214:217], v[102:105]
	ds_write2st64_b64 v124, v[122:123], v[28:29] offset1:32
	v_cvt_pk_bf16_f32 v28, v86, v87
	v_cvt_pk_bf16_f32 v29, v88, v89
	v_mfma_f32_16x16x32_bf16 v[74:77], v[202:205], v[222:225], v[74:77]
	v_lshl_add_u32 v116, v116, 4, v152
	v_or_b32_e32 v117, 16, v151
	v_cvt_pk_bf16_f32 v110, v110, v111
	v_mfma_f32_16x16x32_bf16 v[2:5], v[182:185], v[190:193], v[2:5]
	v_cvt_pk_bf16_f32 v111, v112, v113
	v_bitop3_b32 v112, v126, v151, 16 bitop3:0x1e
	ds_write2st64_b64 v120, v[118:119], v[28:29] offset1:32
	v_mfma_f32_16x16x32_bf16 v[98:101], v[210:213], v[214:217], v[98:101]
	v_cvt_pk_bf16_f32 v28, v82, v83
	v_cvt_pk_bf16_f32 v29, v84, v85
	v_lshl_or_b32 v112, v112, 4, v152
	v_mfma_f32_16x16x32_bf16 v[70:73], v[206:209], v[222:225], v[70:73]
	v_cvt_pk_bf16_f32 v106, v106, v107
	v_cvt_pk_bf16_f32 v107, v108, v109
	v_bitop3_b32 v108, v126, v117, 2 bitop3:0x36
	v_mfma_f32_16x16x32_bf16 v[66:69], v[210:213], v[222:225], v[66:69]
	ds_write2st64_b64 v116, v[114:115], v[28:29] offset1:32
	v_cvt_pk_bf16_f32 v28, v78, v79
	v_cvt_pk_bf16_f32 v29, v80, v81
	v_lshl_add_u32 v108, v108, 4, v152
	v_cvt_pk_bf16_f32 v102, v102, v103
	v_cvt_pk_bf16_f32 v103, v104, v105
	v_bitop3_b32 v104, v126, v117, 4 bitop3:0x36
	ds_write2st64_b64 v112, v[110:111], v[28:29] offset0:16 offset1:48
	v_cvt_pk_bf16_f32 v28, v74, v75
	v_cvt_pk_bf16_f32 v29, v76, v77
	v_lshl_add_u32 v104, v104, 4, v152
	v_cvt_pk_bf16_f32 v98, v98, v99
	v_cvt_pk_bf16_f32 v99, v100, v101
	v_bitop3_b32 v100, v126, v117, 6 bitop3:0x36
	ds_write2st64_b64 v108, v[106:107], v[28:29] offset0:16 offset1:48
	v_cvt_pk_bf16_f32 v28, v70, v71
	v_cvt_pk_bf16_f32 v29, v72, v73
	v_mfma_f32_16x16x32_bf16 v[34:37], v[206:209], v[226:229], v[34:37]
	v_lshl_add_u32 v100, v100, 4, v152
	ds_write2st64_b64 v104, v[102:103], v[28:29] offset0:16 offset1:48
	v_cvt_pk_bf16_f32 v28, v66, v67
	v_mfma_f32_16x16x32_bf16 v[2:5], v[206:209], v[234:237], v[2:5]
	v_cvt_pk_bf16_f32 v29, v68, v69
	ds_write2st64_b64 v100, v[98:99], v[28:29] offset0:16 offset1:48
	s_nop 1
	v_cvt_pk_bf16_f32 v34, v34, v35
	v_mfma_f32_16x16x32_bf16 v[38:41], v[186:189], v[190:193], v[38:41]
	v_cvt_pk_bf16_f32 v35, v36, v37
	s_nop 0
	v_cvt_pk_bf16_f32 v2, v2, v3
	v_cvt_pk_bf16_f32 v3, v4, v5
	v_mfma_f32_16x16x32_bf16 v[6:9], v[178:181], v[190:193], v[6:9]
	ds_write2st64_b64 v104, v[34:35], v[2:3] offset0:80 offset1:112
	v_mfma_f32_16x16x32_bf16 v[28:31], v[210:213], v[226:229], v[30:33]
	v_mfma_f32_16x16x32_bf16 v[2:5], v[210:213], v[234:237], v[38:41]
	v_mfma_f32_16x16x32_bf16 v[62:65], v[198:201], v[144:147], v[62:65]
	s_nop 5
	v_cvt_pk_bf16_f32 v32, v28, v29
	v_cvt_pk_bf16_f32 v33, v30, v31
	v_cvt_pk_bf16_f32 v2, v2, v3
	v_mfma_f32_16x16x32_bf16 v[58:61], v[202:205], v[144:147], v[58:61]
	v_cvt_pk_bf16_f32 v3, v4, v5
	v_cvt_pk_bf16_f32 v62, v62, v63
	v_cvt_pk_bf16_f32 v63, v64, v65
	v_mfma_f32_16x16x32_bf16 v[54:57], v[206:209], v[144:147], v[54:57]
	ds_write2st64_b64 v100, v[32:33], v[2:3] offset0:80 offset1:112
	s_nop 2
	v_cvt_pk_bf16_f32 v58, v58, v59
	v_cvt_pk_bf16_f32 v59, v60, v61
	v_mfma_f32_16x16x32_bf16 v[50:53], v[210:213], v[144:147], v[50:53]
	v_and_b32_e32 v2, 0x1f0, v142
	v_cvt_pk_bf16_f32 v54, v54, v55
	v_cvt_pk_bf16_f32 v55, v56, v57
	v_mfma_f32_16x16x32_bf16 v[46:49], v[198:201], v[226:229], v[46:49]
	v_mfma_f32_16x16x32_bf16 v[42:45], v[202:205], v[226:229], v[42:45]
	s_nop 2
	v_cvt_pk_bf16_f32 v50, v50, v51
	v_cvt_pk_bf16_f32 v51, v52, v53
	s_nop 1
	v_cvt_pk_bf16_f32 v46, v46, v47
	v_mfma_f32_16x16x32_bf16 v[28:31], v[198:201], v[230:233], v[194:197]
	v_cvt_pk_bf16_f32 v47, v48, v49
	v_cvt_pk_bf16_f32 v42, v42, v43
	v_cvt_pk_bf16_f32 v43, v44, v45
	v_mfma_f32_16x16x32_bf16 v[22:25], v[202:205], v[230:233], v[22:25]
	v_mfma_f32_16x16x32_bf16 v[18:21], v[206:209], v[230:233], v[18:21]
	s_nop 2
	v_cvt_pk_bf16_f32 v28, v28, v29
	v_cvt_pk_bf16_f32 v29, v30, v31
	s_nop 1
	v_cvt_pk_bf16_f32 v22, v22, v23
	v_mfma_f32_16x16x32_bf16 v[14:17], v[210:213], v[230:233], v[14:17]
	v_cvt_pk_bf16_f32 v23, v24, v25
	v_cvt_pk_bf16_f32 v18, v18, v19
	v_cvt_pk_bf16_f32 v19, v20, v21
	v_mfma_f32_16x16x32_bf16 v[10:13], v[198:201], v[234:237], v[10:13]
	ds_write2st64_b64 v127, v[62:63], v[28:29] offset0:64 offset1:96
	s_nop 2
	v_cvt_pk_bf16_f32 v14, v14, v15
	v_cvt_pk_bf16_f32 v15, v16, v17
	v_mfma_f32_16x16x32_bf16 v[6:9], v[202:205], v[234:237], v[6:9]
	ds_write2st64_b64 v124, v[58:59], v[22:23] offset0:64 offset1:96
	v_cvt_pk_bf16_f32 v10, v10, v11
	v_cvt_pk_bf16_f32 v11, v12, v13
	ds_write2st64_b64 v120, v[54:55], v[18:19] offset0:64 offset1:96
	ds_write2st64_b64 v116, v[50:51], v[14:15] offset0:64 offset1:96
	s_nop 2
	v_cvt_pk_bf16_f32 v6, v6, v7
	v_cvt_pk_bf16_f32 v7, v8, v9
	ds_write2st64_b64 v112, v[46:47], v[10:11] offset0:80 offset1:112
	ds_write2st64_b64 v108, v[42:43], v[6:7] offset0:80 offset1:112
	s_waitcnt lgkmcnt(0)
	s_barrier

; #define GLDS_STAGE(st, kt_) do { \
;         _Pragma("unroll") for (int i_ = 0; i_ < FI; ++i_) { \
;             glds16(ap + (size_t)(32 * i_) * lda + (kt_) * 64, l3a + (st) + tid * 16 + i_ * 4096); \
;             glds16(bp + (size_t)(32 * i_) * ldb + (kt_) * 64, l3a + (st) + OPB + tid * 16 + i_ * 4096); } } while (0)
; #define GLDS_STAGE(st, kt_) do { \
;         _Pragma("unroll") for (int i_ = 0; i_ < 4; ++i_) { \
;             glds16(ap + (size_t)(64 * i_) * lda + (kt_) * 64, l3a + (st) + tid * 16 + i_ * 8192); \
;             glds16(bp + (size_t)(64 * i_) * ldb + (kt_) * 64, l3a + (st) + 32768 + tid * 16 + i_ * 8192); } } while (0)
; template <class Epi>
; DEV void gemm256_tile(const bf16_t* __restrict__ A, int lda, const bf16_t* __restrict__ Bt, int ldb, int K, unsigned char* lds, const Epi& epi) {
;     ...
;     for (int kt = 0; kt < nk; ++kt) {
;         const int cur = (kt & 1) * 65536;
;         asm volatile("s_waitcnt vmcnt(0)" ::: "memory");
;         __syncthreads();
;         if (kt + 1 < nk) GLDS_STAGE(cur ^ 65536, kt + 1);
; #pragma unroll
;         for (int kh = 0; kh < 2; ++kh) {
;             bf16x8 bfr[4];
;             const int ch = ((kh * 4 + fq) ^ sw) << 4;
; #pragma unroll
;             for (int i = 0; i < 4; ++i) bfr[i] = *(const bf16x8*)(lds + cur + boff + i * 2048 + ch);
; #pragma unroll
;             for (int mh = 0; mh < 2; ++mh) {
;                 bf16x8 af[4];
; #pragma unroll
;                 for (int i = 0; i < 4; ++i) af[i] = *(const bf16x8*)(lds + cur + aoff + (mh * 4 + i) * 2048 + ch);
; #pragma unroll
;                 for (int mi = 0; mi < 4; ++mi)
; #pragma unroll
;                     for (int ni = 0; ni < 4; ++ni) acc[mh * 4 + mi][ni] = __builtin_amdgcn_mfma_f32_16x16x32_bf16(bfr[ni], af[mi], acc[mh * 4 + mi][ni], 0, 0, 0);
;             }
;         }
.LBB0_1003:
	s_and_b32 s48, s25, 0x10000
	s_xor_b32 s49, s48, 0x10000
	v_add_u32_e32 v216, s49, v136
	v_add_u32_e32 v217, s49, v150
	s_waitcnt vmcnt(0) lgkmcnt(0)
	s_barrier
	v_or_b32_e32 v248, s48, v151
	v_add_u32_e32 v249, s48, v148
	v_add_u32_e32 v244, v248, v149
	v_add_u32_e32 v245, v249, v149
	ds_read_b128 v[152:155], v244 offset:32768
	ds_read_b128 v[176:179], v244 offset:34816
	ds_read_b128 v[180:183], v244 offset:36864
	ds_read_b128 v[184:187], v244 offset:38912
	ds_read_b128 v[228:231], v245
	ds_read_b128 v[232:235], v245 offset:2048
	ds_read_b128 v[236:239], v245 offset:4096
	ds_read_b128 v[240:243], v245 offset:6144
	v_readfirstlane_b32 s40, v216
	v_readfirstlane_b32 s44, v217
	v_add_u32_e32 v246, v248, v147
	v_add_u32_e32 v247, v249, v147
	s_mov_b32 m0, s40
	v_lshl_add_u64 v[204:205], v[138:139], 0, s[6:7]
	global_load_lds_dwordx4 v[138:139], off
	s_mov_b32 m0, s44
	v_lshl_add_u64 v[210:211], v[140:141], 0, s[6:7]
	global_load_lds_dwordx4 v[140:141], off
	s_add_i32 s41, s40, 0x2000
	s_add_i32 s45, s44, 0x2000
	s_add_i32 s42, s40, 0x4000
	s_add_i32 s46, s44, 0x4000
	s_add_i32 s43, s40, 0x6000
	s_add_i32 s47, s44, 0x6000
	s_add_i32 s25, s25, 0x10000
	s_waitcnt lgkmcnt(3)
	v_mfma_f32_16x16x32_bf16 v[126:129], v[152:155], v[228:231], v[126:129]
	v_lshl_add_u64 v[206:207], v[138:139], 0, s[8:9]
	v_mfma_f32_16x16x32_bf16 v[122:125], v[176:179], v[228:231], v[122:125]
	v_lshl_add_u64 v[212:213], v[140:141], 0, s[8:9]
	v_mfma_f32_16x16x32_bf16 v[118:121], v[180:183], v[228:231], v[118:121]
	v_lshl_add_u64 v[208:209], v[138:139], 0, s[10:11]
	v_mfma_f32_16x16x32_bf16 v[114:117], v[184:187], v[228:231], v[114:117]
	v_lshl_add_u64 v[214:215], v[140:141], 0, s[10:11]
	s_waitcnt lgkmcnt(2)
	v_mfma_f32_16x16x32_bf16 v[110:113], v[152:155], v[232:235], v[110:113]
	v_mfma_f32_16x16x32_bf16 v[106:109], v[176:179], v[232:235], v[106:109]
	v_mfma_f32_16x16x32_bf16 v[102:105], v[180:183], v[232:235], v[102:105]
	v_mfma_f32_16x16x32_bf16 v[98:101], v[184:187], v[232:235], v[98:101]
	s_waitcnt lgkmcnt(1)
	v_mfma_f32_16x16x32_bf16 v[94:97], v[152:155], v[236:239], v[94:97]
	ds_read_b128 v[228:231], v245 offset:8192
	v_mfma_f32_16x16x32_bf16 v[90:93], v[176:179], v[236:239], v[90:93]
	ds_read_b128 v[232:235], v245 offset:10240
	v_mfma_f32_16x16x32_bf16 v[86:89], v[180:183], v[236:239], v[86:89]
	s_mov_b32 m0, s41
	v_mfma_f32_16x16x32_bf16 v[82:85], v[184:187], v[236:239], v[82:85]
	global_load_lds_dwordx4 v[204:205], off
	s_waitcnt lgkmcnt(2)
	v_mfma_f32_16x16x32_bf16 v[78:81], v[152:155], v[240:243], v[78:81]
	s_mov_b32 m0, s45
	v_mfma_f32_16x16x32_bf16 v[74:77], v[176:179], v[240:243], v[74:77]
	global_load_lds_dwordx4 v[210:211], off
	v_mfma_f32_16x16x32_bf16 v[70:73], v[180:183], v[240:243], v[70:73]
	v_mfma_f32_16x16x32_bf16 v[66:69], v[184:187], v[240:243], v[66:69]
	s_waitcnt lgkmcnt(1)
	v_mfma_f32_16x16x32_bf16 v[62:65], v[152:155], v[228:231], v[62:65]
	ds_read_b128 v[236:239], v245 offset:12288
	v_mfma_f32_16x16x32_bf16 v[58:61], v[176:179], v[228:231], v[58:61]
	ds_read_b128 v[240:243], v245 offset:14336
	v_mfma_f32_16x16x32_bf16 v[54:57], v[180:183], v[228:231], v[54:57]
	s_mov_b32 m0, s42
	v_mfma_f32_16x16x32_bf16 v[50:53], v[184:187], v[228:231], v[50:53]
	global_load_lds_dwordx4 v[206:207], off
	s_waitcnt lgkmcnt(2)
	v_mfma_f32_16x16x32_bf16 v[46:49], v[152:155], v[232:235], v[46:49]
	s_mov_b32 m0, s46
	v_mfma_f32_16x16x32_bf16 v[42:45], v[176:179], v[232:235], v[42:45]
	global_load_lds_dwordx4 v[212:213], off
	v_mfma_f32_16x16x32_bf16 v[34:37], v[180:183], v[232:235], v[34:37]
	v_mfma_f32_16x16x32_bf16 v[30:33], v[184:187], v[232:235], v[30:33]
	s_waitcnt lgkmcnt(1)
	v_mfma_f32_16x16x32_bf16 v[26:29], v[152:155], v[236:239], v[26:29]
	ds_read_b128 v[188:191], v246 offset:32768
	v_mfma_f32_16x16x32_bf16 v[22:25], v[176:179], v[236:239], v[22:25]
	ds_read_b128 v[192:195], v246 offset:34816
	v_mfma_f32_16x16x32_bf16 v[18:21], v[180:183], v[236:239], v[18:21]
	ds_read_b128 v[220:223], v246 offset:36864
	v_mfma_f32_16x16x32_bf16 v[14:17], v[184:187], v[236:239], v[14:17]
	ds_read_b128 v[224:227], v246 offset:38912
	s_waitcnt lgkmcnt(4)
	v_mfma_f32_16x16x32_bf16 v[10:13], v[152:155], v[240:243], v[10:13]
	ds_read_b128 v[228:231], v247
	v_mfma_f32_16x16x32_bf16 v[6:9], v[176:179], v[240:243], v[6:9]
	ds_read_b128 v[232:235], v247 offset:2048
	v_mfma_f32_16x16x32_bf16 v[2:5], v[180:183], v[240:243], v[2:5]
	s_mov_b32 m0, s43
	v_mfma_f32_16x16x32_bf16 v[38:41], v[184:187], v[240:243], v[38:41]
	global_load_lds_dwordx4 v[208:209], off
	s_mov_b32 m0, s47
	v_lshl_add_u64 v[138:139], v[138:139], 0, s[12:13]
	global_load_lds_dwordx4 v[214:215], off
	v_lshl_add_u64 v[140:141], v[140:141], 0, s[12:13]
	s_waitcnt lgkmcnt(1)
	v_mfma_f32_16x16x32_bf16 v[126:129], v[188:191], v[228:231], v[126:129]
	ds_read_b128 v[236:239], v247 offset:4096
	v_mfma_f32_16x16x32_bf16 v[122:125], v[192:195], v[228:231], v[122:125]
	ds_read_b128 v[240:243], v247 offset:6144
	v_mfma_f32_16x16x32_bf16 v[118:121], v[220:223], v[228:231], v[118:121]
	v_mfma_f32_16x16x32_bf16 v[114:117], v[224:227], v[228:231], v[114:117]
	s_waitcnt lgkmcnt(2)
	v_mfma_f32_16x16x32_bf16 v[110:113], v[188:191], v[232:235], v[110:113]
	v_mfma_f32_16x16x32_bf16 v[106:109], v[192:195], v[232:235], v[106:109]
	v_mfma_f32_16x16x32_bf16 v[102:105], v[220:223], v[232:235], v[102:105]
	v_mfma_f32_16x16x32_bf16 v[98:101], v[224:227], v[232:235], v[98:101]
	s_waitcnt lgkmcnt(1)
	v_mfma_f32_16x16x32_bf16 v[94:97], v[188:191], v[236:239], v[94:97]
	ds_read_b128 v[228:231], v247 offset:8192
	v_mfma_f32_16x16x32_bf16 v[90:93], v[192:195], v[236:239], v[90:93]
	ds_read_b128 v[232:235], v247 offset:10240
	v_mfma_f32_16x16x32_bf16 v[86:89], v[220:223], v[236:239], v[86:89]
	v_mfma_f32_16x16x32_bf16 v[82:85], v[224:227], v[236:239], v[82:85]
	s_waitcnt lgkmcnt(2)
; DEV unsigned cvt_pk_bf16(float lo, float hi) { const f32x2_t v = {lo, hi}; const bf16x2_t b = __builtin_convertvector(v, bf16x2_t); return __builtin_bit_cast(unsigned, b); }
; template <class Epi>
; DEV void gemm256_tile(const bf16_t* __restrict__ A, int lda, const bf16_t* __restrict__ Bt, int ldb, int K, unsigned char* lds, const Epi& epi) {
;     ...
;         for (int kh = 0; kh < 2; ++kh) {
;             bf16x8 bfr[4];
;             const int ch = ((kh * 4 + fq) ^ sw) << 4;
; #pragma unroll
;             for (int i = 0; i < 4; ++i) bfr[i] = *(const bf16x8*)(lds + cur + boff + i * 2048 + ch);
; #pragma unroll
;             for (int mh = 0; mh < 2; ++mh) {
;                 bf16x8 af[4];
; #pragma unroll
;                 for (int i = 0; i < 4; ++i) af[i] = *(const bf16x8*)(lds + cur + aoff + (mh * 4 + i) * 2048 + ch);
; #pragma unroll
;                 for (int mi = 0; mi < 4; ++mi)
; #pragma unroll
;                     for (int ni = 0; ni < 4; ++ni) acc[mh * 4 + mi][ni] = __builtin_amdgcn_mfma_f32_16x16x32_bf16(bfr[ni], af[mi], acc[mh * 4 + mi][ni], 0, 0, 0);
;             }
;         }
;     }
;     ...
;     __syncthreads();
;     if constexpr (Epi::STAGE) {
; #pragma unroll
;         for (int mi = 0; mi < 8; ++mi)
; #pragma unroll
;             for (int ni = 0; ni < 4; ++ni) {
;                 const int row = wr * 128 + mi * 16 + fr, col = wc * 64 + ni * 16 + fq * 4;
;                 const f32x4 v = epi.xform(row, col, acc[mi][ni]);
;                 uint2 w; w.x = cvt_pk_bf16(v[0], v[1]); w.y = cvt_pk_bf16(v[2], v[3]);
;                 *(uint2*)(lds + row * 512 + ((((col >> 3) ^ (row & 31)) << 4) | (((col >> 2) & 1) << 3))) = w;
	v_mfma_f32_16x16x32_bf16 v[78:81], v[188:191], v[240:243], v[78:81]
	v_mfma_f32_16x16x32_bf16 v[74:77], v[192:195], v[240:243], v[74:77]
	v_mfma_f32_16x16x32_bf16 v[70:73], v[220:223], v[240:243], v[70:73]
	v_mfma_f32_16x16x32_bf16 v[66:69], v[224:227], v[240:243], v[66:69]
	s_waitcnt lgkmcnt(1)
	v_mfma_f32_16x16x32_bf16 v[62:65], v[188:191], v[228:231], v[62:65]
	ds_read_b128 v[236:239], v247 offset:12288
	v_mfma_f32_16x16x32_bf16 v[58:61], v[192:195], v[228:231], v[58:61]
	ds_read_b128 v[240:243], v247 offset:14336
	v_mfma_f32_16x16x32_bf16 v[54:57], v[220:223], v[228:231], v[54:57]
	v_mfma_f32_16x16x32_bf16 v[50:53], v[224:227], v[228:231], v[50:53]
	s_waitcnt lgkmcnt(2)
	v_mfma_f32_16x16x32_bf16 v[46:49], v[188:191], v[232:235], v[46:49]
	v_mfma_f32_16x16x32_bf16 v[42:45], v[192:195], v[232:235], v[42:45]
	v_mfma_f32_16x16x32_bf16 v[34:37], v[220:223], v[232:235], v[34:37]
	v_mfma_f32_16x16x32_bf16 v[30:33], v[224:227], v[232:235], v[30:33]
	s_waitcnt lgkmcnt(1)
	v_mfma_f32_16x16x32_bf16 v[26:29], v[188:191], v[236:239], v[26:29]
	v_mfma_f32_16x16x32_bf16 v[22:25], v[192:195], v[236:239], v[22:25]
	v_mfma_f32_16x16x32_bf16 v[18:21], v[220:223], v[236:239], v[18:21]
	v_mfma_f32_16x16x32_bf16 v[14:17], v[224:227], v[236:239], v[14:17]
	s_waitcnt lgkmcnt(0)
	v_mfma_f32_16x16x32_bf16 v[10:13], v[188:191], v[240:243], v[10:13]
	v_mfma_f32_16x16x32_bf16 v[6:9], v[192:195], v[240:243], v[6:9]
	v_mfma_f32_16x16x32_bf16 v[2:5], v[220:223], v[240:243], v[2:5]
	v_mfma_f32_16x16x32_bf16 v[38:41], v[224:227], v[240:243], v[38:41]
	s_cmp_eq_u32 s25, 0x1f0000
	s_cbranch_scc0 .LBB0_1003
	v_or_b32_e32 v172, 0x18000, v151
	v_add_u32_e32 v156, v172, v149
	s_waitcnt vmcnt(0)
	s_barrier
	ds_read_b128 v[138:141], v156
	ds_read_b128 v[152:155], v156 offset:2048
	ds_read_b128 v[176:179], v156 offset:4096
	ds_read_b128 v[180:183], v156 offset:6144
	v_add_u32_e32 v173, 0x10000, v148
	v_add_u32_e32 v188, v173, v149
	ds_read_b128 v[148:151], v188
	s_waitcnt lgkmcnt(0)
	v_mfma_f32_16x16x32_bf16 v[126:129], v[138:141], v[148:151], v[126:129]
	s_sext_i32_i8 s14, s24
	s_lshl_b32 s24, s14, 8
	s_lshl_b64 s[16:17], s[16:17], 21
	v_mfma_f32_16x16x32_bf16 v[122:125], v[152:155], v[148:151], v[122:125]
	s_ashr_i32 s25, s24, 31
	s_add_u32 s14, s4, s16
	s_addc_u32 s15, s5, s17
	v_mfma_f32_16x16x32_bf16 v[118:121], v[176:179], v[148:151], v[118:121]
	s_lshl_b64 s[16:17], s[24:25], 2
	v_lshl_add_u64 v[156:157], v[130:131], 0, s[18:19]
	s_add_u32 s16, s14, s16
	v_mfma_f32_16x16x32_bf16 v[114:117], v[180:183], v[148:151], v[114:117]
	ds_read_b128 v[148:151], v188 offset:2048
	s_addc_u32 s17, s15, s17
	s_mov_b32 s18, 0
	s_waitcnt lgkmcnt(0)
	v_mfma_f32_16x16x32_bf16 v[110:113], v[138:141], v[148:151], v[110:113]
	v_mfma_f32_16x16x32_bf16 v[106:109], v[152:155], v[148:151], v[106:109]
	v_mfma_f32_16x16x32_bf16 v[102:105], v[176:179], v[148:151], v[102:105]
	v_mfma_f32_16x16x32_bf16 v[98:101], v[180:183], v[148:151], v[98:101]
	ds_read_b128 v[148:151], v188 offset:4096
	s_waitcnt lgkmcnt(0)
	v_mfma_f32_16x16x32_bf16 v[94:97], v[138:141], v[148:151], v[94:97]
	v_mfma_f32_16x16x32_bf16 v[90:93], v[152:155], v[148:151], v[90:93]
	v_mfma_f32_16x16x32_bf16 v[86:89], v[176:179], v[148:151], v[86:89]
	v_mfma_f32_16x16x32_bf16 v[82:85], v[180:183], v[148:151], v[82:85]
	ds_read_b128 v[148:151], v188 offset:6144
	s_waitcnt lgkmcnt(0)
	v_mfma_f32_16x16x32_bf16 v[78:81], v[138:141], v[148:151], v[78:81]
	v_mfma_f32_16x16x32_bf16 v[74:77], v[152:155], v[148:151], v[74:77]
	v_mfma_f32_16x16x32_bf16 v[70:73], v[176:179], v[148:151], v[70:73]
	v_mfma_f32_16x16x32_bf16 v[66:69], v[180:183], v[148:151], v[66:69]
	ds_read_b128 v[148:151], v188 offset:8192
	ds_read_b128 v[184:187], v188 offset:10240
	s_waitcnt lgkmcnt(1)
	v_mfma_f32_16x16x32_bf16 v[62:65], v[138:141], v[148:151], v[62:65]
	v_mfma_f32_16x16x32_bf16 v[58:61], v[152:155], v[148:151], v[58:61]
	v_mfma_f32_16x16x32_bf16 v[54:57], v[176:179], v[148:151], v[54:57]
	v_mfma_f32_16x16x32_bf16 v[50:53], v[180:183], v[148:151], v[50:53]
	ds_read_b128 v[148:151], v188 offset:12288
	s_waitcnt lgkmcnt(1)
	v_mfma_f32_16x16x32_bf16 v[46:49], v[138:141], v[184:187], v[46:49]
	v_mfma_f32_16x16x32_bf16 v[42:45], v[152:155], v[184:187], v[42:45]
	v_mfma_f32_16x16x32_bf16 v[34:37], v[176:179], v[184:187], v[34:37]
	v_mfma_f32_16x16x32_bf16 v[30:33], v[180:183], v[184:187], v[30:33]
	ds_read_b128 v[184:187], v188 offset:14336
	s_waitcnt lgkmcnt(1)
	v_mfma_f32_16x16x32_bf16 v[188:191], v[138:141], v[148:151], v[26:29]
	s_nop 2
	v_add_u32_e32 v29, v172, v147
	ds_read_b128 v[192:195], v29
	ds_read_b128 v[196:199], v29 offset:2048
	ds_read_b128 v[200:203], v29 offset:4096
	ds_read_b128 v[204:207], v29 offset:6144
	v_add_u32_e32 v29, v173, v147
	v_mfma_f32_16x16x32_bf16 v[22:25], v[152:155], v[148:151], v[22:25]
	v_and_b32_e32 v28, 0xc0, v142
	v_lshl_or_b32 v145, v145, 2, v28
	v_lshlrev_b32_e32 v28, 3, v144
	v_mfma_f32_16x16x32_bf16 v[18:21], v[176:179], v[148:151], v[18:21]
	v_lshl_add_u64 v[26:27], s[24:25], 1, v[156:157]
	v_mfma_f32_16x16x32_bf16 v[14:17], v[180:183], v[148:151], v[14:17]
	ds_read_b128 v[148:151], v29
	ds_read_b128 v[208:211], v29 offset:2048
	ds_read_b128 v[212:215], v29 offset:4096
	ds_read_b128 v[216:219], v29 offset:6144
	s_waitcnt lgkmcnt(3)
	v_mfma_f32_16x16x32_bf16 v[126:129], v[192:195], v[148:151], v[126:129]
	v_mfma_f32_16x16x32_bf16 v[122:125], v[196:199], v[148:151], v[122:125]
	s_waitcnt lgkmcnt(1)
	v_mfma_f32_16x16x32_bf16 v[94:97], v[192:195], v[212:215], v[94:97]
	v_mfma_f32_16x16x32_bf16 v[10:13], v[138:141], v[184:187], v[10:13]
	ds_read_b128 v[138:141], v29 offset:8192
	ds_read_b128 v[220:223], v29 offset:10240
	ds_read_b128 v[224:227], v29 offset:12288
	ds_read_b128 v[228:231], v29 offset:14336
	v_lshlrev_b32_e32 v29, 9, v146
	v_and_or_b32 v144, v28, 8, v29
	v_mfma_f32_16x16x32_bf16 v[118:121], v[200:203], v[148:151], v[118:121]
	v_cvt_pk_bf16_f32 v28, v126, v127
	v_lshrrev_b32_e32 v126, 3, v145
	v_xor_b32_e32 v127, v126, v143
	v_mfma_f32_16x16x32_bf16 v[90:93], v[196:199], v[212:215], v[90:93]
	v_cvt_pk_bf16_f32 v29, v128, v129
	v_lshl_or_b32 v127, v127, 4, v144
	v_cvt_pk_bf16_f32 v122, v122, v123
	v_mfma_f32_16x16x32_bf16 v[114:117], v[204:207], v[148:151], v[114:117]
	v_cvt_pk_bf16_f32 v123, v124, v125
	v_bitop3_b32 v124, v126, v143, 2 bitop3:0x36
	v_cvt_pk_bf16_f32 v94, v94, v95
	v_mfma_f32_16x16x32_bf16 v[86:89], v[200:203], v[212:215], v[86:89]
	v_cvt_pk_bf16_f32 v95, v96, v97
	s_waitcnt lgkmcnt(0)
	s_barrier
; DEV unsigned cvt_pk_bf16(float lo, float hi) { const f32x2_t v = {lo, hi}; const bf16x2_t b = __builtin_convertvector(v, bf16x2_t); return __builtin_bit_cast(unsigned, b); }
; template <class Epi>
; DEV void gemm256_tile(const bf16_t* __restrict__ A, int lda, const bf16_t* __restrict__ Bt, int ldb, int K, unsigned char* lds, const Epi& epi) {
;     ...
;                 for (int mi = 0; mi < 4; ++mi)
; #pragma unroll
;                     for (int ni = 0; ni < 4; ++ni) acc[mh * 4 + mi][ni] = __builtin_amdgcn_mfma_f32_16x16x32_bf16(bfr[ni], af[mi], acc[mh * 4 + mi][ni], 0, 0, 0);
;             }
;         }
;     }
;     ...
;     __syncthreads();
;     if constexpr (Epi::STAGE) {
; #pragma unroll
;         for (int mi = 0; mi < 8; ++mi)
; #pragma unroll
;             for (int ni = 0; ni < 4; ++ni) {
;                 const int row = wr * 128 + mi * 16 + fr, col = wc * 64 + ni * 16 + fq * 4;
;                 const f32x4 v = epi.xform(row, col, acc[mi][ni]);
;                 uint2 w; w.x = cvt_pk_bf16(v[0], v[1]); w.y = cvt_pk_bf16(v[2], v[3]);
;                 *(uint2*)(lds + row * 512 + ((((col >> 3) ^ (row & 31)) << 4) | (((col >> 2) & 1) << 3))) = w;
;             }
;         __syncthreads();
	v_mfma_f32_16x16x32_bf16 v[110:113], v[192:195], v[208:211], v[110:113]
	v_lshl_add_u32 v124, v124, 4, v144
	v_cvt_pk_bf16_f32 v118, v118, v119
	v_mfma_f32_16x16x32_bf16 v[82:85], v[204:207], v[212:215], v[82:85]
	v_cvt_pk_bf16_f32 v119, v120, v121
	v_bitop3_b32 v120, v126, v143, 4 bitop3:0x36
	ds_write2st64_b64 v127, v[28:29], v[94:95] offset1:32
	v_mfma_f32_16x16x32_bf16 v[106:109], v[196:199], v[208:211], v[106:109]
	v_cvt_pk_bf16_f32 v28, v90, v91
	v_cvt_pk_bf16_f32 v29, v92, v93
	v_lshl_add_u32 v120, v120, 4, v144
	v_mfma_f32_16x16x32_bf16 v[78:81], v[192:195], v[216:219], v[78:81]
	v_cvt_pk_bf16_f32 v114, v114, v115
	v_cvt_pk_bf16_f32 v115, v116, v117
	v_bitop3_b32 v116, v126, v143, 6 bitop3:0x36
	v_mfma_f32_16x16x32_bf16 v[102:105], v[200:203], v[208:211], v[102:105]
	ds_write2st64_b64 v124, v[122:123], v[28:29] offset1:32
	v_cvt_pk_bf16_f32 v28, v86, v87
	v_cvt_pk_bf16_f32 v29, v88, v89
	v_mfma_f32_16x16x32_bf16 v[74:77], v[196:199], v[216:219], v[74:77]
	v_lshl_add_u32 v116, v116, 4, v144
	v_or_b32_e32 v117, 16, v143
	v_cvt_pk_bf16_f32 v110, v110, v111
	v_mfma_f32_16x16x32_bf16 v[2:5], v[176:179], v[184:187], v[2:5]
	v_cvt_pk_bf16_f32 v111, v112, v113
	v_bitop3_b32 v112, v126, v143, 16 bitop3:0x1e
	ds_write2st64_b64 v120, v[118:119], v[28:29] offset1:32
	v_mfma_f32_16x16x32_bf16 v[98:101], v[204:207], v[208:211], v[98:101]
	v_cvt_pk_bf16_f32 v28, v82, v83
	v_cvt_pk_bf16_f32 v29, v84, v85
	v_lshl_or_b32 v112, v112, 4, v144
	v_mfma_f32_16x16x32_bf16 v[70:73], v[200:203], v[216:219], v[70:73]
	v_cvt_pk_bf16_f32 v106, v106, v107
	v_cvt_pk_bf16_f32 v107, v108, v109
	v_bitop3_b32 v108, v126, v117, 2 bitop3:0x36
	v_mfma_f32_16x16x32_bf16 v[66:69], v[204:207], v[216:219], v[66:69]
	ds_write2st64_b64 v116, v[114:115], v[28:29] offset1:32
	v_cvt_pk_bf16_f32 v28, v78, v79
	v_cvt_pk_bf16_f32 v29, v80, v81
	v_lshl_add_u32 v108, v108, 4, v144
	v_cvt_pk_bf16_f32 v102, v102, v103
	v_cvt_pk_bf16_f32 v103, v104, v105
	v_bitop3_b32 v104, v126, v117, 4 bitop3:0x36
	ds_write2st64_b64 v112, v[110:111], v[28:29] offset0:16 offset1:48
	v_cvt_pk_bf16_f32 v28, v74, v75
	v_cvt_pk_bf16_f32 v29, v76, v77
	v_lshl_add_u32 v104, v104, 4, v144
	v_cvt_pk_bf16_f32 v98, v98, v99
	v_cvt_pk_bf16_f32 v99, v100, v101
	v_bitop3_b32 v100, v126, v117, 6 bitop3:0x36
	ds_write2st64_b64 v108, v[106:107], v[28:29] offset0:16 offset1:48
	v_cvt_pk_bf16_f32 v28, v70, v71
	v_cvt_pk_bf16_f32 v29, v72, v73
	v_mfma_f32_16x16x32_bf16 v[34:37], v[200:203], v[220:223], v[34:37]
	v_lshl_add_u32 v100, v100, 4, v144
	ds_write2st64_b64 v104, v[102:103], v[28:29] offset0:16 offset1:48
	v_cvt_pk_bf16_f32 v28, v66, v67
	v_mfma_f32_16x16x32_bf16 v[2:5], v[200:203], v[228:231], v[2:5]
	v_cvt_pk_bf16_f32 v29, v68, v69
	ds_write2st64_b64 v100, v[98:99], v[28:29] offset0:16 offset1:48
	s_nop 1
	v_cvt_pk_bf16_f32 v34, v34, v35
	v_mfma_f32_16x16x32_bf16 v[38:41], v[180:183], v[184:187], v[38:41]
	v_cvt_pk_bf16_f32 v35, v36, v37
	s_nop 0
	v_cvt_pk_bf16_f32 v2, v2, v3
	v_cvt_pk_bf16_f32 v3, v4, v5
	v_mfma_f32_16x16x32_bf16 v[6:9], v[152:155], v[184:187], v[6:9]
	ds_write2st64_b64 v104, v[34:35], v[2:3] offset0:80 offset1:112
	v_mfma_f32_16x16x32_bf16 v[28:31], v[204:207], v[220:223], v[30:33]
	v_mfma_f32_16x16x32_bf16 v[2:5], v[204:207], v[228:231], v[38:41]
	v_mfma_f32_16x16x32_bf16 v[62:65], v[192:195], v[138:141], v[62:65]
	s_nop 5
	v_cvt_pk_bf16_f32 v32, v28, v29
	v_cvt_pk_bf16_f32 v33, v30, v31
	v_cvt_pk_bf16_f32 v2, v2, v3
	v_mfma_f32_16x16x32_bf16 v[58:61], v[196:199], v[138:141], v[58:61]
	v_cvt_pk_bf16_f32 v3, v4, v5
	v_cvt_pk_bf16_f32 v62, v62, v63
	v_cvt_pk_bf16_f32 v63, v64, v65
	v_mfma_f32_16x16x32_bf16 v[54:57], v[200:203], v[138:141], v[54:57]
	ds_write2st64_b64 v100, v[32:33], v[2:3] offset0:80 offset1:112
	s_nop 2
	v_cvt_pk_bf16_f32 v58, v58, v59
	v_cvt_pk_bf16_f32 v59, v60, v61
	v_mfma_f32_16x16x32_bf16 v[50:53], v[204:207], v[138:141], v[50:53]
	v_and_b32_e32 v2, 0x1f0, v136
	v_cvt_pk_bf16_f32 v54, v54, v55
	v_cvt_pk_bf16_f32 v55, v56, v57
	v_mfma_f32_16x16x32_bf16 v[46:49], v[192:195], v[220:223], v[46:49]
	v_mfma_f32_16x16x32_bf16 v[42:45], v[196:199], v[220:223], v[42:45]
	s_nop 2
	v_cvt_pk_bf16_f32 v50, v50, v51
	v_cvt_pk_bf16_f32 v51, v52, v53
	s_nop 1
	v_cvt_pk_bf16_f32 v46, v46, v47
	v_mfma_f32_16x16x32_bf16 v[28:31], v[192:195], v[224:227], v[188:191]
	v_cvt_pk_bf16_f32 v47, v48, v49
	v_cvt_pk_bf16_f32 v42, v42, v43
	v_cvt_pk_bf16_f32 v43, v44, v45
	v_mfma_f32_16x16x32_bf16 v[22:25], v[196:199], v[224:227], v[22:25]
	v_mfma_f32_16x16x32_bf16 v[18:21], v[200:203], v[224:227], v[18:21]
	s_nop 2
	v_cvt_pk_bf16_f32 v28, v28, v29
	v_cvt_pk_bf16_f32 v29, v30, v31
	s_nop 1
	v_cvt_pk_bf16_f32 v22, v22, v23
	v_mfma_f32_16x16x32_bf16 v[14:17], v[204:207], v[224:227], v[14:17]
	v_cvt_pk_bf16_f32 v23, v24, v25
	v_cvt_pk_bf16_f32 v18, v18, v19
	v_cvt_pk_bf16_f32 v19, v20, v21
	v_mfma_f32_16x16x32_bf16 v[10:13], v[192:195], v[228:231], v[10:13]
	ds_write2st64_b64 v127, v[62:63], v[28:29] offset0:64 offset1:96
	s_nop 2
	v_cvt_pk_bf16_f32 v14, v14, v15
	v_cvt_pk_bf16_f32 v15, v16, v17
	v_mfma_f32_16x16x32_bf16 v[6:9], v[196:199], v[228:231], v[6:9]
	ds_write2st64_b64 v124, v[58:59], v[22:23] offset0:64 offset1:96
	v_cvt_pk_bf16_f32 v10, v10, v11
	v_cvt_pk_bf16_f32 v11, v12, v13
	ds_write2st64_b64 v120, v[54:55], v[18:19] offset0:64 offset1:96
	ds_write2st64_b64 v116, v[50:51], v[14:15] offset0:64 offset1:96
	s_nop 2
	v_cvt_pk_bf16_f32 v6, v6, v7
	v_cvt_pk_bf16_f32 v7, v8, v9
	ds_write2st64_b64 v112, v[46:47], v[10:11] offset0:80 offset1:112
	ds_write2st64_b64 v108, v[42:43], v[6:7] offset0:80 offset1:112
	s_waitcnt lgkmcnt(0)
	s_barrier

; #define GLDS_STAGE(st, kt_) do { \
;         _Pragma("unroll") for (int i_ = 0; i_ < FI; ++i_) { \
;             glds16(ap + (size_t)(32 * i_) * lda + (kt_) * 64, l3a + (st) + tid * 16 + i_ * 4096); \
;             glds16(bp + (size_t)(32 * i_) * ldb + (kt_) * 64, l3a + (st) + OPB + tid * 16 + i_ * 4096); } } while (0)
; #define GLDS_STAGE(st, kt_) do { \
;         _Pragma("unroll") for (int i_ = 0; i_ < 4; ++i_) { \
;             glds16(ap + (size_t)(64 * i_) * lda + (kt_) * 64, l3a + (st) + tid * 16 + i_ * 8192); \
;             glds16(bp + (size_t)(64 * i_) * ldb + (kt_) * 64, l3a + (st) + 32768 + tid * 16 + i_ * 8192); } } while (0)
; template <class Epi>
; DEV void gemm256_tile(const bf16_t* __restrict__ A, int lda, const bf16_t* __restrict__ Bt, int ldb, int K, unsigned char* lds, const Epi& epi) {
;     ...
;     for (int kt = 0; kt < nk; ++kt) {
;         const int cur = (kt & 1) * 65536;
;         asm volatile("s_waitcnt vmcnt(0)" ::: "memory");
;         __syncthreads();
;         if (kt + 1 < nk) GLDS_STAGE(cur ^ 65536, kt + 1);
; #pragma unroll
;         for (int kh = 0; kh < 2; ++kh) {
;             bf16x8 bfr[4];
;             const int ch = ((kh * 4 + fq) ^ sw) << 4;
; #pragma unroll
;             for (int i = 0; i < 4; ++i) bfr[i] = *(const bf16x8*)(lds + cur + boff + i * 2048 + ch);
; #pragma unroll
;             for (int mh = 0; mh < 2; ++mh) {
;                 bf16x8 af[4];
; #pragma unroll
;                 for (int i = 0; i < 4; ++i) af[i] = *(const bf16x8*)(lds + cur + aoff + (mh * 4 + i) * 2048 + ch);
; #pragma unroll
;                 for (int mi = 0; mi < 4; ++mi)
; #pragma unroll
;                     for (int ni = 0; ni < 4; ++ni) acc[mh * 4 + mi][ni] = __builtin_amdgcn_mfma_f32_16x16x32_bf16(bfr[ni], af[mi], acc[mh * 4 + mi][ni], 0, 0, 0);
;             }
;         }
.LBB0_1236:
	s_and_b32 s48, s21, 0x10000
	s_xor_b32 s49, s48, 0x10000
	v_add_u32_e32 v216, s49, v138
	v_add_u32_e32 v217, s49, v150
	s_waitcnt vmcnt(0) lgkmcnt(0)
	s_barrier
	v_or_b32_e32 v248, s48, v153
	v_add_u32_e32 v249, s48, v151
	v_add_u32_e32 v244, v248, v152
	v_add_u32_e32 v245, v249, v152
	ds_read_b128 v[154:157], v244 offset:32768
	ds_read_b128 v[170:173], v244 offset:34816
	ds_read_b128 v[174:177], v244 offset:36864
	ds_read_b128 v[178:181], v244 offset:38912
	ds_read_b128 v[228:231], v245
	ds_read_b128 v[232:235], v245 offset:2048
	ds_read_b128 v[236:239], v245 offset:4096
	ds_read_b128 v[240:243], v245 offset:6144
	v_readfirstlane_b32 s40, v216
	v_readfirstlane_b32 s44, v217
	v_add_u32_e32 v246, v248, v149
	v_add_u32_e32 v247, v249, v149
	s_mov_b32 m0, s40
	v_lshl_add_u64 v[204:205], v[140:141], 0, s[4:5]
	global_load_lds_dwordx4 v[140:141], off
	s_mov_b32 m0, s44
	v_lshl_add_u64 v[210:211], v[142:143], 0, s[4:5]
	global_load_lds_dwordx4 v[142:143], off
	s_add_i32 s41, s40, 0x2000
	s_add_i32 s45, s44, 0x2000
	s_add_i32 s42, s40, 0x4000
	s_add_i32 s46, s44, 0x4000
	s_add_i32 s43, s40, 0x6000
	s_add_i32 s47, s44, 0x6000
	s_add_i32 s21, s21, 0x10000
	s_waitcnt lgkmcnt(3)
	v_mfma_f32_16x16x32_bf16 v[126:129], v[154:157], v[228:231], v[126:129]
	v_lshl_add_u64 v[206:207], v[140:141], 0, s[6:7]
	v_mfma_f32_16x16x32_bf16 v[122:125], v[170:173], v[228:231], v[122:125]
	v_lshl_add_u64 v[212:213], v[142:143], 0, s[6:7]
	v_mfma_f32_16x16x32_bf16 v[118:121], v[174:177], v[228:231], v[118:121]
	v_lshl_add_u64 v[208:209], v[140:141], 0, s[8:9]
	v_mfma_f32_16x16x32_bf16 v[114:117], v[178:181], v[228:231], v[114:117]
	v_lshl_add_u64 v[214:215], v[142:143], 0, s[8:9]
	s_waitcnt lgkmcnt(2)
	v_mfma_f32_16x16x32_bf16 v[110:113], v[154:157], v[232:235], v[110:113]
	v_mfma_f32_16x16x32_bf16 v[106:109], v[170:173], v[232:235], v[106:109]
	v_mfma_f32_16x16x32_bf16 v[102:105], v[174:177], v[232:235], v[102:105]
	v_mfma_f32_16x16x32_bf16 v[98:101], v[178:181], v[232:235], v[98:101]
	s_waitcnt lgkmcnt(1)
	v_mfma_f32_16x16x32_bf16 v[94:97], v[154:157], v[236:239], v[94:97]
	ds_read_b128 v[228:231], v245 offset:8192
	v_mfma_f32_16x16x32_bf16 v[90:93], v[170:173], v[236:239], v[90:93]
	ds_read_b128 v[232:235], v245 offset:10240
	v_mfma_f32_16x16x32_bf16 v[86:89], v[174:177], v[236:239], v[86:89]
	s_mov_b32 m0, s41
	v_mfma_f32_16x16x32_bf16 v[82:85], v[178:181], v[236:239], v[82:85]
	global_load_lds_dwordx4 v[204:205], off
	s_waitcnt lgkmcnt(2)
	v_mfma_f32_16x16x32_bf16 v[78:81], v[154:157], v[240:243], v[78:81]
	s_mov_b32 m0, s45
	v_mfma_f32_16x16x32_bf16 v[74:77], v[170:173], v[240:243], v[74:77]
	global_load_lds_dwordx4 v[210:211], off
	v_mfma_f32_16x16x32_bf16 v[70:73], v[174:177], v[240:243], v[70:73]
	v_mfma_f32_16x16x32_bf16 v[66:69], v[178:181], v[240:243], v[66:69]
	s_waitcnt lgkmcnt(1)
	v_mfma_f32_16x16x32_bf16 v[62:65], v[154:157], v[228:231], v[62:65]
	ds_read_b128 v[236:239], v245 offset:12288
	v_mfma_f32_16x16x32_bf16 v[58:61], v[170:173], v[228:231], v[58:61]
	ds_read_b128 v[240:243], v245 offset:14336
	v_mfma_f32_16x16x32_bf16 v[54:57], v[174:177], v[228:231], v[54:57]
	s_mov_b32 m0, s42
	v_mfma_f32_16x16x32_bf16 v[50:53], v[178:181], v[228:231], v[50:53]
	global_load_lds_dwordx4 v[206:207], off
	s_waitcnt lgkmcnt(2)
	v_mfma_f32_16x16x32_bf16 v[46:49], v[154:157], v[232:235], v[46:49]
	s_mov_b32 m0, s46
	v_mfma_f32_16x16x32_bf16 v[42:45], v[170:173], v[232:235], v[42:45]
	global_load_lds_dwordx4 v[212:213], off
	v_mfma_f32_16x16x32_bf16 v[34:37], v[174:177], v[232:235], v[34:37]
	v_mfma_f32_16x16x32_bf16 v[30:33], v[178:181], v[232:235], v[30:33]
	s_waitcnt lgkmcnt(1)
	v_mfma_f32_16x16x32_bf16 v[26:29], v[154:157], v[236:239], v[26:29]
	ds_read_b128 v[182:185], v246 offset:32768
	v_mfma_f32_16x16x32_bf16 v[22:25], v[170:173], v[236:239], v[22:25]
	ds_read_b128 v[186:189], v246 offset:34816
	v_mfma_f32_16x16x32_bf16 v[18:21], v[174:177], v[236:239], v[18:21]
	ds_read_b128 v[220:223], v246 offset:36864
	v_mfma_f32_16x16x32_bf16 v[14:17], v[178:181], v[236:239], v[14:17]
	ds_read_b128 v[224:227], v246 offset:38912
	s_waitcnt lgkmcnt(4)
	v_mfma_f32_16x16x32_bf16 v[10:13], v[154:157], v[240:243], v[10:13]
	ds_read_b128 v[228:231], v247
	v_mfma_f32_16x16x32_bf16 v[6:9], v[170:173], v[240:243], v[6:9]
	ds_read_b128 v[232:235], v247 offset:2048
	v_mfma_f32_16x16x32_bf16 v[2:5], v[174:177], v[240:243], v[2:5]
	s_mov_b32 m0, s43
	v_mfma_f32_16x16x32_bf16 v[38:41], v[178:181], v[240:243], v[38:41]
	global_load_lds_dwordx4 v[208:209], off
	s_mov_b32 m0, s47
	v_lshl_add_u64 v[140:141], v[140:141], 0, s[10:11]
	global_load_lds_dwordx4 v[214:215], off
	v_lshl_add_u64 v[142:143], v[142:143], 0, s[10:11]
	s_waitcnt lgkmcnt(1)
	v_mfma_f32_16x16x32_bf16 v[126:129], v[182:185], v[228:231], v[126:129]
	ds_read_b128 v[236:239], v247 offset:4096
	v_mfma_f32_16x16x32_bf16 v[122:125], v[186:189], v[228:231], v[122:125]
	ds_read_b128 v[240:243], v247 offset:6144
	v_mfma_f32_16x16x32_bf16 v[118:121], v[220:223], v[228:231], v[118:121]
	v_mfma_f32_16x16x32_bf16 v[114:117], v[224:227], v[228:231], v[114:117]
	s_waitcnt lgkmcnt(2)
	v_mfma_f32_16x16x32_bf16 v[110:113], v[182:185], v[232:235], v[110:113]
	v_mfma_f32_16x16x32_bf16 v[106:109], v[186:189], v[232:235], v[106:109]
	v_mfma_f32_16x16x32_bf16 v[102:105], v[220:223], v[232:235], v[102:105]
	v_mfma_f32_16x16x32_bf16 v[98:101], v[224:227], v[232:235], v[98:101]
	s_waitcnt lgkmcnt(1)
	v_mfma_f32_16x16x32_bf16 v[94:97], v[182:185], v[236:239], v[94:97]
	ds_read_b128 v[228:231], v247 offset:8192
	v_mfma_f32_16x16x32_bf16 v[90:93], v[186:189], v[236:239], v[90:93]
	ds_read_b128 v[232:235], v247 offset:10240
	v_mfma_f32_16x16x32_bf16 v[86:89], v[220:223], v[236:239], v[86:89]
	v_mfma_f32_16x16x32_bf16 v[82:85], v[224:227], v[236:239], v[82:85]
	s_waitcnt lgkmcnt(2)
; DEV unsigned cvt_pk_bf16(float lo, float hi) { const f32x2_t v = {lo, hi}; const bf16x2_t b = __builtin_convertvector(v, bf16x2_t); return __builtin_bit_cast(unsigned, b); }
; template <class Epi>
; DEV void gemm256_tile(const bf16_t* __restrict__ A, int lda, const bf16_t* __restrict__ Bt, int ldb, int K, unsigned char* lds, const Epi& epi) {
;     ...
;         for (int kh = 0; kh < 2; ++kh) {
;             bf16x8 bfr[4];
;             const int ch = ((kh * 4 + fq) ^ sw) << 4;
; #pragma unroll
;             for (int i = 0; i < 4; ++i) bfr[i] = *(const bf16x8*)(lds + cur + boff + i * 2048 + ch);
; #pragma unroll
;             for (int mh = 0; mh < 2; ++mh) {
;                 bf16x8 af[4];
; #pragma unroll
;                 for (int i = 0; i < 4; ++i) af[i] = *(const bf16x8*)(lds + cur + aoff + (mh * 4 + i) * 2048 + ch);
; #pragma unroll
;                 for (int mi = 0; mi < 4; ++mi)
; #pragma unroll
;                     for (int ni = 0; ni < 4; ++ni) acc[mh * 4 + mi][ni] = __builtin_amdgcn_mfma_f32_16x16x32_bf16(bfr[ni], af[mi], acc[mh * 4 + mi][ni], 0, 0, 0);
;             }
;         }
;     }
;     ...
;     __syncthreads();
;     if constexpr (Epi::STAGE) {
; #pragma unroll
;         for (int mi = 0; mi < 8; ++mi)
; #pragma unroll
;             for (int ni = 0; ni < 4; ++ni) {
;                 const int row = wr * 128 + mi * 16 + fr, col = wc * 64 + ni * 16 + fq * 4;
;                 const f32x4 v = epi.xform(row, col, acc[mi][ni]);
;                 uint2 w; w.x = cvt_pk_bf16(v[0], v[1]); w.y = cvt_pk_bf16(v[2], v[3]);
;                 *(uint2*)(lds + row * 512 + ((((col >> 3) ^ (row & 31)) << 4) | (((col >> 2) & 1) << 3))) = w;
	v_mfma_f32_16x16x32_bf16 v[78:81], v[182:185], v[240:243], v[78:81]
	v_mfma_f32_16x16x32_bf16 v[74:77], v[186:189], v[240:243], v[74:77]
	v_mfma_f32_16x16x32_bf16 v[70:73], v[220:223], v[240:243], v[70:73]
	v_mfma_f32_16x16x32_bf16 v[66:69], v[224:227], v[240:243], v[66:69]
	s_waitcnt lgkmcnt(1)
	v_mfma_f32_16x16x32_bf16 v[62:65], v[182:185], v[228:231], v[62:65]
	ds_read_b128 v[236:239], v247 offset:12288
	v_mfma_f32_16x16x32_bf16 v[58:61], v[186:189], v[228:231], v[58:61]
	ds_read_b128 v[240:243], v247 offset:14336
	v_mfma_f32_16x16x32_bf16 v[54:57], v[220:223], v[228:231], v[54:57]
	v_mfma_f32_16x16x32_bf16 v[50:53], v[224:227], v[228:231], v[50:53]
	s_waitcnt lgkmcnt(2)
	v_mfma_f32_16x16x32_bf16 v[46:49], v[182:185], v[232:235], v[46:49]
	v_mfma_f32_16x16x32_bf16 v[42:45], v[186:189], v[232:235], v[42:45]
	v_mfma_f32_16x16x32_bf16 v[34:37], v[220:223], v[232:235], v[34:37]
	v_mfma_f32_16x16x32_bf16 v[30:33], v[224:227], v[232:235], v[30:33]
	s_waitcnt lgkmcnt(1)
	v_mfma_f32_16x16x32_bf16 v[26:29], v[182:185], v[236:239], v[26:29]
	v_mfma_f32_16x16x32_bf16 v[22:25], v[186:189], v[236:239], v[22:25]
	v_mfma_f32_16x16x32_bf16 v[18:21], v[220:223], v[236:239], v[18:21]
	v_mfma_f32_16x16x32_bf16 v[14:17], v[224:227], v[236:239], v[14:17]
	s_waitcnt lgkmcnt(0)
	v_mfma_f32_16x16x32_bf16 v[10:13], v[182:185], v[240:243], v[10:13]
	v_mfma_f32_16x16x32_bf16 v[6:9], v[186:189], v[240:243], v[6:9]
	v_mfma_f32_16x16x32_bf16 v[2:5], v[220:223], v[240:243], v[2:5]
	v_mfma_f32_16x16x32_bf16 v[38:41], v[224:227], v[240:243], v[38:41]
	s_cmp_eq_u32 s21, 0x1f0000
	s_cbranch_scc0 .LBB0_1236
	v_or_b32_e32 v186, 0x18000, v153
	v_add_u32_e32 v202, 0x10000, v151
	v_add_u32_e32 v174, v186, v152
	v_add_u32_e32 v182, v202, v152
	s_waitcnt vmcnt(0)
	s_barrier
	ds_read_b128 v[140:143], v174
	ds_read_b128 v[154:157], v174 offset:2048
	ds_read_b128 v[150:153], v182
	ds_read_b128 v[170:173], v174 offset:4096
	ds_read_b128 v[174:177], v174 offset:6144
	s_waitcnt lgkmcnt(2)
	v_mfma_f32_16x16x32_bf16 v[126:129], v[140:143], v[150:153], v[126:129]
	s_sext_i32_i8 s14, s20
	s_lshl_b32 s20, s14, 8
	s_ashr_i32 s21, s20, 31
	v_mfma_f32_16x16x32_bf16 v[122:125], v[154:157], v[150:153], v[122:125]
	s_waitcnt lgkmcnt(1)
	v_mfma_f32_16x16x32_bf16 v[118:121], v[170:173], v[150:153], v[118:121]
	s_waitcnt lgkmcnt(0)
	v_mfma_f32_16x16x32_bf16 v[114:117], v[174:177], v[150:153], v[114:117]
	ds_read_b128 v[150:153], v182 offset:2048
	s_waitcnt lgkmcnt(0)
	v_mfma_f32_16x16x32_bf16 v[110:113], v[140:143], v[150:153], v[110:113]
	v_mfma_f32_16x16x32_bf16 v[106:109], v[154:157], v[150:153], v[106:109]
	v_mfma_f32_16x16x32_bf16 v[102:105], v[170:173], v[150:153], v[102:105]
	v_mfma_f32_16x16x32_bf16 v[98:101], v[174:177], v[150:153], v[98:101]
	ds_read_b128 v[150:153], v182 offset:4096
	s_waitcnt lgkmcnt(0)
	v_mfma_f32_16x16x32_bf16 v[94:97], v[140:143], v[150:153], v[94:97]
	v_mfma_f32_16x16x32_bf16 v[90:93], v[154:157], v[150:153], v[90:93]
	v_mfma_f32_16x16x32_bf16 v[86:89], v[170:173], v[150:153], v[86:89]
	v_mfma_f32_16x16x32_bf16 v[82:85], v[174:177], v[150:153], v[82:85]
	ds_read_b128 v[150:153], v182 offset:6144
	s_waitcnt lgkmcnt(0)
	v_mfma_f32_16x16x32_bf16 v[78:81], v[140:143], v[150:153], v[78:81]
	v_mfma_f32_16x16x32_bf16 v[74:77], v[154:157], v[150:153], v[74:77]
	v_mfma_f32_16x16x32_bf16 v[70:73], v[170:173], v[150:153], v[70:73]
	v_mfma_f32_16x16x32_bf16 v[66:69], v[174:177], v[150:153], v[66:69]
	ds_read_b128 v[150:153], v182 offset:8192
	ds_read_b128 v[178:181], v182 offset:10240
	s_waitcnt lgkmcnt(1)
	v_mfma_f32_16x16x32_bf16 v[62:65], v[140:143], v[150:153], v[62:65]
	v_mfma_f32_16x16x32_bf16 v[58:61], v[154:157], v[150:153], v[58:61]
	v_mfma_f32_16x16x32_bf16 v[54:57], v[170:173], v[150:153], v[54:57]
	v_mfma_f32_16x16x32_bf16 v[50:53], v[174:177], v[150:153], v[50:53]
	ds_read_b128 v[150:153], v182 offset:12288
	s_waitcnt lgkmcnt(1)
	v_mfma_f32_16x16x32_bf16 v[46:49], v[140:143], v[178:181], v[46:49]
	v_mfma_f32_16x16x32_bf16 v[42:45], v[154:157], v[178:181], v[42:45]
	v_mfma_f32_16x16x32_bf16 v[34:37], v[170:173], v[178:181], v[34:37]
	v_mfma_f32_16x16x32_bf16 v[30:33], v[174:177], v[178:181], v[30:33]
	ds_read_b128 v[178:181], v182 offset:14336
	s_waitcnt lgkmcnt(1)
	v_mfma_f32_16x16x32_bf16 v[182:185], v[140:143], v[150:153], v[26:29]
	s_nop 2
	v_add_u32_e32 v29, v186, v149
	ds_read_b128 v[186:189], v29
	ds_read_b128 v[190:193], v29 offset:2048
	ds_read_b128 v[194:197], v29 offset:4096
	ds_read_b128 v[198:201], v29 offset:6144
	v_add_u32_e32 v29, v202, v149
	v_mfma_f32_16x16x32_bf16 v[22:25], v[154:157], v[150:153], v[22:25]
	v_and_b32_e32 v28, 0xc0, v144
	v_lshl_or_b32 v147, v147, 2, v28
	v_lshlrev_b32_e32 v28, 3, v146
	v_mfma_f32_16x16x32_bf16 v[18:21], v[170:173], v[150:153], v[18:21]
	v_lshl_add_u64 v[26:27], v[132:133], 0, s[12:13]
	v_lshl_add_u64 v[26:27], s[20:21], 1, v[26:27]
	s_mov_b32 s12, 0
	v_mfma_f32_16x16x32_bf16 v[14:17], v[174:177], v[150:153], v[14:17]
	ds_read_b128 v[150:153], v29
	ds_read_b128 v[202:205], v29 offset:2048
	ds_read_b128 v[206:209], v29 offset:4096
	ds_read_b128 v[210:213], v29 offset:6144
	s_waitcnt lgkmcnt(3)
	v_mfma_f32_16x16x32_bf16 v[126:129], v[186:189], v[150:153], v[126:129]
	v_mfma_f32_16x16x32_bf16 v[122:125], v[190:193], v[150:153], v[122:125]
	s_waitcnt lgkmcnt(1)
	v_mfma_f32_16x16x32_bf16 v[94:97], v[186:189], v[206:209], v[94:97]
	v_mfma_f32_16x16x32_bf16 v[10:13], v[140:143], v[178:181], v[10:13]
	ds_read_b128 v[140:143], v29 offset:8192
	ds_read_b128 v[214:217], v29 offset:10240
	ds_read_b128 v[218:221], v29 offset:12288
	ds_read_b128 v[222:225], v29 offset:14336
	v_lshlrev_b32_e32 v29, 9, v148
	v_and_or_b32 v146, v28, 8, v29
	v_mfma_f32_16x16x32_bf16 v[118:121], v[194:197], v[150:153], v[118:121]
	v_cvt_pk_bf16_f32 v28, v126, v127
	v_lshrrev_b32_e32 v126, 3, v147
	v_xor_b32_e32 v127, v126, v145
	v_mfma_f32_16x16x32_bf16 v[90:93], v[190:193], v[206:209], v[90:93]
	v_cvt_pk_bf16_f32 v29, v128, v129
	v_lshl_or_b32 v127, v127, 4, v146
	v_cvt_pk_bf16_f32 v122, v122, v123
	v_mfma_f32_16x16x32_bf16 v[114:117], v[198:201], v[150:153], v[114:117]
	v_cvt_pk_bf16_f32 v123, v124, v125
	v_bitop3_b32 v124, v126, v145, 2 bitop3:0x36
	v_cvt_pk_bf16_f32 v94, v94, v95
	v_mfma_f32_16x16x32_bf16 v[86:89], v[194:197], v[206:209], v[86:89]
	v_cvt_pk_bf16_f32 v95, v96, v97
	s_waitcnt lgkmcnt(0)
	s_barrier
; DEV unsigned cvt_pk_bf16(float lo, float hi) { const f32x2_t v = {lo, hi}; const bf16x2_t b = __builtin_convertvector(v, bf16x2_t); return __builtin_bit_cast(unsigned, b); }
; template <class Epi>
; DEV void gemm256_tile(const bf16_t* __restrict__ A, int lda, const bf16_t* __restrict__ Bt, int ldb, int K, unsigned char* lds, const Epi& epi) {
;     ...
;                 for (int mi = 0; mi < 4; ++mi)
; #pragma unroll
;                     for (int ni = 0; ni < 4; ++ni) acc[mh * 4 + mi][ni] = __builtin_amdgcn_mfma_f32_16x16x32_bf16(bfr[ni], af[mi], acc[mh * 4 + mi][ni], 0, 0, 0);
;             }
;         }
;     }
;     ...
;     __syncthreads();
;     if constexpr (Epi::STAGE) {
; #pragma unroll
;         for (int mi = 0; mi < 8; ++mi)
; #pragma unroll
;             for (int ni = 0; ni < 4; ++ni) {
;                 const int row = wr * 128 + mi * 16 + fr, col = wc * 64 + ni * 16 + fq * 4;
;                 const f32x4 v = epi.xform(row, col, acc[mi][ni]);
;                 uint2 w; w.x = cvt_pk_bf16(v[0], v[1]); w.y = cvt_pk_bf16(v[2], v[3]);
;                 *(uint2*)(lds + row * 512 + ((((col >> 3) ^ (row & 31)) << 4) | (((col >> 2) & 1) << 3))) = w;
;             }
;         __syncthreads();
	v_mfma_f32_16x16x32_bf16 v[110:113], v[186:189], v[202:205], v[110:113]
	v_lshl_add_u32 v124, v124, 4, v146
	v_cvt_pk_bf16_f32 v118, v118, v119
	v_mfma_f32_16x16x32_bf16 v[82:85], v[198:201], v[206:209], v[82:85]
	v_cvt_pk_bf16_f32 v119, v120, v121
	v_bitop3_b32 v120, v126, v145, 4 bitop3:0x36
	ds_write2st64_b64 v127, v[28:29], v[94:95] offset1:32
	v_mfma_f32_16x16x32_bf16 v[106:109], v[190:193], v[202:205], v[106:109]
	v_cvt_pk_bf16_f32 v28, v90, v91
	v_cvt_pk_bf16_f32 v29, v92, v93
	v_lshl_add_u32 v120, v120, 4, v146
	v_mfma_f32_16x16x32_bf16 v[78:81], v[186:189], v[210:213], v[78:81]
	v_cvt_pk_bf16_f32 v114, v114, v115
	v_cvt_pk_bf16_f32 v115, v116, v117
	v_bitop3_b32 v116, v126, v145, 6 bitop3:0x36
	v_mfma_f32_16x16x32_bf16 v[102:105], v[194:197], v[202:205], v[102:105]
	ds_write2st64_b64 v124, v[122:123], v[28:29] offset1:32
	v_cvt_pk_bf16_f32 v28, v86, v87
	v_cvt_pk_bf16_f32 v29, v88, v89
	v_mfma_f32_16x16x32_bf16 v[74:77], v[190:193], v[210:213], v[74:77]
	v_lshl_add_u32 v116, v116, 4, v146
	v_or_b32_e32 v117, 16, v145
	v_cvt_pk_bf16_f32 v110, v110, v111
	v_mfma_f32_16x16x32_bf16 v[2:5], v[170:173], v[178:181], v[2:5]
	v_cvt_pk_bf16_f32 v111, v112, v113
	v_bitop3_b32 v112, v126, v145, 16 bitop3:0x1e
	ds_write2st64_b64 v120, v[118:119], v[28:29] offset1:32
	v_mfma_f32_16x16x32_bf16 v[98:101], v[198:201], v[202:205], v[98:101]
	v_cvt_pk_bf16_f32 v28, v82, v83
	v_cvt_pk_bf16_f32 v29, v84, v85
	v_lshl_or_b32 v112, v112, 4, v146
	v_mfma_f32_16x16x32_bf16 v[70:73], v[194:197], v[210:213], v[70:73]
	v_cvt_pk_bf16_f32 v106, v106, v107
	v_cvt_pk_bf16_f32 v107, v108, v109
	v_bitop3_b32 v108, v126, v117, 2 bitop3:0x36
	v_mfma_f32_16x16x32_bf16 v[66:69], v[198:201], v[210:213], v[66:69]
	ds_write2st64_b64 v116, v[114:115], v[28:29] offset1:32
	v_cvt_pk_bf16_f32 v28, v78, v79
	v_cvt_pk_bf16_f32 v29, v80, v81
	v_lshl_add_u32 v108, v108, 4, v146
	v_cvt_pk_bf16_f32 v102, v102, v103
	v_cvt_pk_bf16_f32 v103, v104, v105
	v_bitop3_b32 v104, v126, v117, 4 bitop3:0x36
	ds_write2st64_b64 v112, v[110:111], v[28:29] offset0:16 offset1:48
	v_cvt_pk_bf16_f32 v28, v74, v75
	v_cvt_pk_bf16_f32 v29, v76, v77
	v_lshl_add_u32 v104, v104, 4, v146
	v_cvt_pk_bf16_f32 v98, v98, v99
	v_cvt_pk_bf16_f32 v99, v100, v101
	v_bitop3_b32 v100, v126, v117, 6 bitop3:0x36
	ds_write2st64_b64 v108, v[106:107], v[28:29] offset0:16 offset1:48
	v_cvt_pk_bf16_f32 v28, v70, v71
	v_cvt_pk_bf16_f32 v29, v72, v73
	v_mfma_f32_16x16x32_bf16 v[34:37], v[194:197], v[214:217], v[34:37]
	v_lshl_add_u32 v100, v100, 4, v146
	ds_write2st64_b64 v104, v[102:103], v[28:29] offset0:16 offset1:48
	v_cvt_pk_bf16_f32 v28, v66, v67
	v_mfma_f32_16x16x32_bf16 v[2:5], v[194:197], v[222:225], v[2:5]
	v_cvt_pk_bf16_f32 v29, v68, v69
	ds_write2st64_b64 v100, v[98:99], v[28:29] offset0:16 offset1:48
	s_nop 1
	v_cvt_pk_bf16_f32 v34, v34, v35
	v_mfma_f32_16x16x32_bf16 v[38:41], v[174:177], v[178:181], v[38:41]
	v_cvt_pk_bf16_f32 v35, v36, v37
	s_nop 0
	v_cvt_pk_bf16_f32 v2, v2, v3
	v_cvt_pk_bf16_f32 v3, v4, v5
	v_mfma_f32_16x16x32_bf16 v[6:9], v[154:157], v[178:181], v[6:9]
	ds_write2st64_b64 v104, v[34:35], v[2:3] offset0:80 offset1:112
	v_mfma_f32_16x16x32_bf16 v[28:31], v[198:201], v[214:217], v[30:33]
	v_mfma_f32_16x16x32_bf16 v[2:5], v[198:201], v[222:225], v[38:41]
	v_mfma_f32_16x16x32_bf16 v[62:65], v[186:189], v[140:143], v[62:65]
	s_nop 5
	v_cvt_pk_bf16_f32 v32, v28, v29
	v_cvt_pk_bf16_f32 v33, v30, v31
	v_cvt_pk_bf16_f32 v2, v2, v3
	v_mfma_f32_16x16x32_bf16 v[58:61], v[190:193], v[140:143], v[58:61]
	v_cvt_pk_bf16_f32 v3, v4, v5
	v_cvt_pk_bf16_f32 v62, v62, v63
	v_cvt_pk_bf16_f32 v63, v64, v65
	v_mfma_f32_16x16x32_bf16 v[54:57], v[194:197], v[140:143], v[54:57]
	ds_write2st64_b64 v100, v[32:33], v[2:3] offset0:80 offset1:112
	s_nop 2
	v_cvt_pk_bf16_f32 v58, v58, v59
	v_cvt_pk_bf16_f32 v59, v60, v61
	v_mfma_f32_16x16x32_bf16 v[50:53], v[198:201], v[140:143], v[50:53]
	v_and_b32_e32 v2, 0x1f0, v138
	v_cvt_pk_bf16_f32 v54, v54, v55
	v_cvt_pk_bf16_f32 v55, v56, v57
	v_mfma_f32_16x16x32_bf16 v[46:49], v[186:189], v[214:217], v[46:49]
	v_mfma_f32_16x16x32_bf16 v[42:45], v[190:193], v[214:217], v[42:45]
	s_nop 2
	v_cvt_pk_bf16_f32 v50, v50, v51
	v_cvt_pk_bf16_f32 v51, v52, v53
	s_nop 1
	v_cvt_pk_bf16_f32 v46, v46, v47
	v_mfma_f32_16x16x32_bf16 v[28:31], v[186:189], v[218:221], v[182:185]
	v_cvt_pk_bf16_f32 v47, v48, v49
	v_cvt_pk_bf16_f32 v42, v42, v43
	v_cvt_pk_bf16_f32 v43, v44, v45
	v_mfma_f32_16x16x32_bf16 v[22:25], v[190:193], v[218:221], v[22:25]
	v_mfma_f32_16x16x32_bf16 v[18:21], v[194:197], v[218:221], v[18:21]
	s_nop 2
	v_cvt_pk_bf16_f32 v28, v28, v29
	v_cvt_pk_bf16_f32 v29, v30, v31
	s_nop 1
	v_cvt_pk_bf16_f32 v22, v22, v23
	v_mfma_f32_16x16x32_bf16 v[14:17], v[198:201], v[218:221], v[14:17]
	v_cvt_pk_bf16_f32 v23, v24, v25
	v_cvt_pk_bf16_f32 v18, v18, v19
	v_cvt_pk_bf16_f32 v19, v20, v21
	v_mfma_f32_16x16x32_bf16 v[10:13], v[186:189], v[222:225], v[10:13]
	ds_write2st64_b64 v127, v[62:63], v[28:29] offset0:64 offset1:96
	s_nop 2
	v_cvt_pk_bf16_f32 v14, v14, v15
	v_cvt_pk_bf16_f32 v15, v16, v17
	v_mfma_f32_16x16x32_bf16 v[6:9], v[190:193], v[222:225], v[6:9]
	ds_write2st64_b64 v124, v[58:59], v[22:23] offset0:64 offset1:96
	v_cvt_pk_bf16_f32 v10, v10, v11
	v_cvt_pk_bf16_f32 v11, v12, v13
	ds_write2st64_b64 v120, v[54:55], v[18:19] offset0:64 offset1:96
	ds_write2st64_b64 v116, v[50:51], v[14:15] offset0:64 offset1:96
	s_nop 2
	v_cvt_pk_bf16_f32 v6, v6, v7
	v_cvt_pk_bf16_f32 v7, v8, v9
	ds_write2st64_b64 v112, v[46:47], v[10:11] offset0:80 offset1:112
	ds_write2st64_b64 v108, v[42:43], v[6:7] offset0:80 offset1:112
	s_waitcnt lgkmcnt(0)
	s_barrier

; #define GLDS_STAGE(st, kt_) do { \
;         _Pragma("unroll") for (int i_ = 0; i_ < FI; ++i_) { \
;             glds16(ap + (size_t)(32 * i_) * lda + (kt_) * 64, l3a + (st) + tid * 16 + i_ * 4096); \
;             glds16(bp + (size_t)(32 * i_) * ldb + (kt_) * 64, l3a + (st) + OPB + tid * 16 + i_ * 4096); } } while (0)
; #define GLDS_STAGE(st, kt_) do { \
;         _Pragma("unroll") for (int i_ = 0; i_ < 4; ++i_) { \
;             glds16(ap + (size_t)(64 * i_) * lda + (kt_) * 64, l3a + (st) + tid * 16 + i_ * 8192); \
;             glds16(bp + (size_t)(64 * i_) * ldb + (kt_) * 64, l3a + (st) + 32768 + tid * 16 + i_ * 8192); } } while (0)
; template <class Epi>
; DEV void gemm256_tile(const bf16_t* __restrict__ A, int lda, const bf16_t* __restrict__ Bt, int ldb, int K, unsigned char* lds, const Epi& epi) {
;     ...
;     for (int kt = 0; kt < nk; ++kt) {
;         const int cur = (kt & 1) * 65536;
;         asm volatile("s_waitcnt vmcnt(0)" ::: "memory");
;         __syncthreads();
;         if (kt + 1 < nk) GLDS_STAGE(cur ^ 65536, kt + 1);
; #pragma unroll
;         for (int kh = 0; kh < 2; ++kh) {
;             bf16x8 bfr[4];
;             const int ch = ((kh * 4 + fq) ^ sw) << 4;
; #pragma unroll
;             for (int i = 0; i < 4; ++i) bfr[i] = *(const bf16x8*)(lds + cur + boff + i * 2048 + ch);
; #pragma unroll
;             for (int mh = 0; mh < 2; ++mh) {
;                 bf16x8 af[4];
; #pragma unroll
;                 for (int i = 0; i < 4; ++i) af[i] = *(const bf16x8*)(lds + cur + aoff + (mh * 4 + i) * 2048 + ch);
; #pragma unroll
;                 for (int mi = 0; mi < 4; ++mi)
; #pragma unroll
;                     for (int ni = 0; ni < 4; ++ni) acc[mh * 4 + mi][ni] = __builtin_amdgcn_mfma_f32_16x16x32_bf16(bfr[ni], af[mi], acc[mh * 4 + mi][ni], 0, 0, 0);
;             }
;         }
.LBB0_1466:
	s_and_b32 s48, s21, 0x10000
	s_xor_b32 s49, s48, 0x10000
	v_add_u32_e32 v216, s49, v140
	v_add_u32_e32 v217, s49, v153
	s_waitcnt vmcnt(0) lgkmcnt(0)
	s_barrier
	v_or_b32_e32 v248, s48, v155
	v_add_u32_e32 v249, s48, v152
	v_add_u32_e32 v244, v248, v154
	v_add_u32_e32 v245, v249, v154
	ds_read_b128 v[162:165], v244 offset:32768
	ds_read_b128 v[166:169], v244 offset:34816
	ds_read_b128 v[170:173], v244 offset:36864
	ds_read_b128 v[174:177], v244 offset:38912
	ds_read_b128 v[228:231], v245
	ds_read_b128 v[232:235], v245 offset:2048
	ds_read_b128 v[236:239], v245 offset:4096
	ds_read_b128 v[240:243], v245 offset:6144
	v_readfirstlane_b32 s40, v216
	v_readfirstlane_b32 s44, v217
	v_add_u32_e32 v246, v248, v151
	v_add_u32_e32 v247, v249, v151
	s_mov_b32 m0, s40
	v_lshl_add_u64 v[204:205], v[142:143], 0, s[4:5]
	global_load_lds_dwordx4 v[142:143], off
	s_mov_b32 m0, s44
	v_lshl_add_u64 v[210:211], v[144:145], 0, s[4:5]
	global_load_lds_dwordx4 v[144:145], off
	s_add_i32 s41, s40, 0x2000
	s_add_i32 s45, s44, 0x2000
	s_add_i32 s42, s40, 0x4000
	s_add_i32 s46, s44, 0x4000
	s_add_i32 s43, s40, 0x6000
	s_add_i32 s47, s44, 0x6000
	s_add_i32 s21, s21, 0x10000
	s_waitcnt lgkmcnt(3)
	v_mfma_f32_16x16x32_bf16 v[126:129], v[162:165], v[228:231], v[126:129]
	v_lshl_add_u64 v[206:207], v[142:143], 0, s[6:7]
	v_mfma_f32_16x16x32_bf16 v[122:125], v[166:169], v[228:231], v[122:125]
	v_lshl_add_u64 v[212:213], v[144:145], 0, s[6:7]
	v_mfma_f32_16x16x32_bf16 v[118:121], v[170:173], v[228:231], v[118:121]
	v_lshl_add_u64 v[208:209], v[142:143], 0, s[8:9]
	v_mfma_f32_16x16x32_bf16 v[114:117], v[174:177], v[228:231], v[114:117]
	v_lshl_add_u64 v[214:215], v[144:145], 0, s[8:9]
	s_waitcnt lgkmcnt(2)
	v_mfma_f32_16x16x32_bf16 v[110:113], v[162:165], v[232:235], v[110:113]
	v_mfma_f32_16x16x32_bf16 v[106:109], v[166:169], v[232:235], v[106:109]
	v_mfma_f32_16x16x32_bf16 v[102:105], v[170:173], v[232:235], v[102:105]
	v_mfma_f32_16x16x32_bf16 v[98:101], v[174:177], v[232:235], v[98:101]
	s_waitcnt lgkmcnt(1)
	v_mfma_f32_16x16x32_bf16 v[94:97], v[162:165], v[236:239], v[94:97]
	ds_read_b128 v[228:231], v245 offset:8192
	v_mfma_f32_16x16x32_bf16 v[90:93], v[166:169], v[236:239], v[90:93]
	ds_read_b128 v[232:235], v245 offset:10240
	v_mfma_f32_16x16x32_bf16 v[86:89], v[170:173], v[236:239], v[86:89]
	s_mov_b32 m0, s41
	v_mfma_f32_16x16x32_bf16 v[82:85], v[174:177], v[236:239], v[82:85]
	global_load_lds_dwordx4 v[204:205], off
	s_waitcnt lgkmcnt(2)
	v_mfma_f32_16x16x32_bf16 v[78:81], v[162:165], v[240:243], v[78:81]
	s_mov_b32 m0, s45
	v_mfma_f32_16x16x32_bf16 v[74:77], v[166:169], v[240:243], v[74:77]
	global_load_lds_dwordx4 v[210:211], off
	v_mfma_f32_16x16x32_bf16 v[70:73], v[170:173], v[240:243], v[70:73]
	v_mfma_f32_16x16x32_bf16 v[66:69], v[174:177], v[240:243], v[66:69]
	s_waitcnt lgkmcnt(1)
	v_mfma_f32_16x16x32_bf16 v[62:65], v[162:165], v[228:231], v[62:65]
	ds_read_b128 v[236:239], v245 offset:12288
	v_mfma_f32_16x16x32_bf16 v[58:61], v[166:169], v[228:231], v[58:61]
	ds_read_b128 v[240:243], v245 offset:14336
	v_mfma_f32_16x16x32_bf16 v[54:57], v[170:173], v[228:231], v[54:57]
	s_mov_b32 m0, s42
	v_mfma_f32_16x16x32_bf16 v[50:53], v[174:177], v[228:231], v[50:53]
	global_load_lds_dwordx4 v[206:207], off
	s_waitcnt lgkmcnt(2)
	v_mfma_f32_16x16x32_bf16 v[46:49], v[162:165], v[232:235], v[46:49]
	s_mov_b32 m0, s46
	v_mfma_f32_16x16x32_bf16 v[42:45], v[166:169], v[232:235], v[42:45]
	global_load_lds_dwordx4 v[212:213], off
	v_mfma_f32_16x16x32_bf16 v[34:37], v[170:173], v[232:235], v[34:37]
	v_mfma_f32_16x16x32_bf16 v[30:33], v[174:177], v[232:235], v[30:33]
	s_waitcnt lgkmcnt(1)
	v_mfma_f32_16x16x32_bf16 v[26:29], v[162:165], v[236:239], v[26:29]
	ds_read_b128 v[178:181], v246 offset:32768
	v_mfma_f32_16x16x32_bf16 v[22:25], v[166:169], v[236:239], v[22:25]
	ds_read_b128 v[182:185], v246 offset:34816
	v_mfma_f32_16x16x32_bf16 v[18:21], v[170:173], v[236:239], v[18:21]
	ds_read_b128 v[220:223], v246 offset:36864
	v_mfma_f32_16x16x32_bf16 v[14:17], v[174:177], v[236:239], v[14:17]
	ds_read_b128 v[224:227], v246 offset:38912
	s_waitcnt lgkmcnt(4)
	v_mfma_f32_16x16x32_bf16 v[10:13], v[162:165], v[240:243], v[10:13]
	ds_read_b128 v[228:231], v247
	v_mfma_f32_16x16x32_bf16 v[6:9], v[166:169], v[240:243], v[6:9]
	ds_read_b128 v[232:235], v247 offset:2048
	v_mfma_f32_16x16x32_bf16 v[2:5], v[170:173], v[240:243], v[2:5]
	s_mov_b32 m0, s43
	v_mfma_f32_16x16x32_bf16 v[38:41], v[174:177], v[240:243], v[38:41]
	global_load_lds_dwordx4 v[208:209], off
	s_mov_b32 m0, s47
	v_lshl_add_u64 v[142:143], v[142:143], 0, s[10:11]
	global_load_lds_dwordx4 v[214:215], off
	v_lshl_add_u64 v[144:145], v[144:145], 0, s[10:11]
	s_waitcnt lgkmcnt(1)
	v_mfma_f32_16x16x32_bf16 v[126:129], v[178:181], v[228:231], v[126:129]
	ds_read_b128 v[236:239], v247 offset:4096
	v_mfma_f32_16x16x32_bf16 v[122:125], v[182:185], v[228:231], v[122:125]
	ds_read_b128 v[240:243], v247 offset:6144
	v_mfma_f32_16x16x32_bf16 v[118:121], v[220:223], v[228:231], v[118:121]
	v_mfma_f32_16x16x32_bf16 v[114:117], v[224:227], v[228:231], v[114:117]
	s_waitcnt lgkmcnt(2)
	v_mfma_f32_16x16x32_bf16 v[110:113], v[178:181], v[232:235], v[110:113]
	v_mfma_f32_16x16x32_bf16 v[106:109], v[182:185], v[232:235], v[106:109]
	v_mfma_f32_16x16x32_bf16 v[102:105], v[220:223], v[232:235], v[102:105]
	v_mfma_f32_16x16x32_bf16 v[98:101], v[224:227], v[232:235], v[98:101]
	s_waitcnt lgkmcnt(1)
	v_mfma_f32_16x16x32_bf16 v[94:97], v[178:181], v[236:239], v[94:97]
	ds_read_b128 v[228:231], v247 offset:8192
	v_mfma_f32_16x16x32_bf16 v[90:93], v[182:185], v[236:239], v[90:93]
	ds_read_b128 v[232:235], v247 offset:10240
	v_mfma_f32_16x16x32_bf16 v[86:89], v[220:223], v[236:239], v[86:89]
	v_mfma_f32_16x16x32_bf16 v[82:85], v[224:227], v[236:239], v[82:85]
	s_waitcnt lgkmcnt(2)
; #define GLDS_STAGE(st, kt_) do { \
;         _Pragma("unroll") for (int i_ = 0; i_ < FI; ++i_) { \
;             glds16(ap + (size_t)(32 * i_) * lda + (kt_) * 64, l3a + (st) + tid * 16 + i_ * 4096); \
;             glds16(bp + (size_t)(32 * i_) * ldb + (kt_) * 64, l3a + (st) + OPB + tid * 16 + i_ * 4096); } } while (0)
; #define GLDS_STAGE(st, kt_) do { \
;         _Pragma("unroll") for (int i_ = 0; i_ < 4; ++i_) { \
;             glds16(ap + (size_t)(64 * i_) * lda + (kt_) * 64, l3a + (st) + tid * 16 + i_ * 8192); \
;             glds16(bp + (size_t)(64 * i_) * ldb + (kt_) * 64, l3a + (st) + 32768 + tid * 16 + i_ * 8192); } } while (0)
; template <class Epi>
; DEV void gemm256_tile(const bf16_t* __restrict__ A, int lda, const bf16_t* __restrict__ Bt, int ldb, int K, unsigned char* lds, const Epi& epi) {
;     ...
;     for (int kt = 0; kt < nk; ++kt) {
;         const int cur = (kt & 1) * 65536;
;         asm volatile("s_waitcnt vmcnt(0)" ::: "memory");
;         __syncthreads();
;         if (kt + 1 < nk) GLDS_STAGE(cur ^ 65536, kt + 1);
; #pragma unroll
;         for (int kh = 0; kh < 2; ++kh) {
;             bf16x8 bfr[4];
;             const int ch = ((kh * 4 + fq) ^ sw) << 4;
; #pragma unroll
;             for (int i = 0; i < 4; ++i) bfr[i] = *(const bf16x8*)(lds + cur + boff + i * 2048 + ch);
; #pragma unroll
;             for (int mh = 0; mh < 2; ++mh) {
;                 bf16x8 af[4];
; #pragma unroll
;                 for (int i = 0; i < 4; ++i) af[i] = *(const bf16x8*)(lds + cur + aoff + (mh * 4 + i) * 2048 + ch);
; #pragma unroll
;                 for (int mi = 0; mi < 4; ++mi)
; #pragma unroll
;                     for (int ni = 0; ni < 4; ++ni) acc[mh * 4 + mi][ni] = __builtin_amdgcn_mfma_f32_16x16x32_bf16(bfr[ni], af[mi], acc[mh * 4 + mi][ni], 0, 0, 0);
;             }
;         }
;     }
;     ...
;     __syncthreads();
	v_mfma_f32_16x16x32_bf16 v[78:81], v[178:181], v[240:243], v[78:81]
	v_mfma_f32_16x16x32_bf16 v[74:77], v[182:185], v[240:243], v[74:77]
	v_mfma_f32_16x16x32_bf16 v[70:73], v[220:223], v[240:243], v[70:73]
	v_mfma_f32_16x16x32_bf16 v[66:69], v[224:227], v[240:243], v[66:69]
	s_waitcnt lgkmcnt(1)
	v_mfma_f32_16x16x32_bf16 v[62:65], v[178:181], v[228:231], v[62:65]
	ds_read_b128 v[236:239], v247 offset:12288
	v_mfma_f32_16x16x32_bf16 v[58:61], v[182:185], v[228:231], v[58:61]
	ds_read_b128 v[240:243], v247 offset:14336
	v_mfma_f32_16x16x32_bf16 v[54:57], v[220:223], v[228:231], v[54:57]
	v_mfma_f32_16x16x32_bf16 v[50:53], v[224:227], v[228:231], v[50:53]
	s_waitcnt lgkmcnt(2)
	v_mfma_f32_16x16x32_bf16 v[46:49], v[178:181], v[232:235], v[46:49]
	v_mfma_f32_16x16x32_bf16 v[42:45], v[182:185], v[232:235], v[42:45]
	v_mfma_f32_16x16x32_bf16 v[34:37], v[220:223], v[232:235], v[34:37]
	v_mfma_f32_16x16x32_bf16 v[30:33], v[224:227], v[232:235], v[30:33]
	s_waitcnt lgkmcnt(1)
	v_mfma_f32_16x16x32_bf16 v[26:29], v[178:181], v[236:239], v[26:29]
	v_mfma_f32_16x16x32_bf16 v[22:25], v[182:185], v[236:239], v[22:25]
	v_mfma_f32_16x16x32_bf16 v[18:21], v[220:223], v[236:239], v[18:21]
	v_mfma_f32_16x16x32_bf16 v[14:17], v[224:227], v[236:239], v[14:17]
	s_waitcnt lgkmcnt(0)
	v_mfma_f32_16x16x32_bf16 v[10:13], v[178:181], v[240:243], v[10:13]
	v_mfma_f32_16x16x32_bf16 v[6:9], v[182:185], v[240:243], v[6:9]
	v_mfma_f32_16x16x32_bf16 v[2:5], v[220:223], v[240:243], v[2:5]
	v_mfma_f32_16x16x32_bf16 v[38:41], v[224:227], v[240:243], v[38:41]
	s_cmp_eq_u32 s21, 0x1f0000
	s_cbranch_scc0 .LBB0_1466
	v_or_b32_e32 v184, 0x18000, v155
	v_add_u32_e32 v156, v184, v154
	s_waitcnt vmcnt(0)
	s_barrier
	ds_read_b128 v[142:145], v156
	ds_read_b128 v[162:165], v156 offset:2048
	ds_read_b128 v[166:169], v156 offset:4096
	ds_read_b128 v[170:173], v156 offset:6144
	v_add_u32_e32 v198, 0x10000, v152
	v_add_u32_e32 v178, v198, v154
	ds_read_b128 v[152:155], v178
	s_waitcnt lgkmcnt(0)
	v_mfma_f32_16x16x32_bf16 v[126:129], v[142:145], v[152:155], v[126:129]
	s_sext_i32_i8 s14, s20
	s_lshl_b32 s20, s14, 8
	s_ashr_i32 s21, s20, 31
	v_mfma_f32_16x16x32_bf16 v[122:125], v[162:165], v[152:155], v[122:125]
	v_lshl_add_u64 v[156:157], v[134:135], 0, s[12:13]
	v_lshl_add_u64 v[182:183], v[130:131], 0, s[12:13]
	s_lshl_b64 s[12:13], s[20:21], 1
	v_mfma_f32_16x16x32_bf16 v[118:121], v[166:169], v[152:155], v[118:121]
	v_lshlrev_b32_e32 v148, 3, v148
	v_lshlrev_b32_e32 v150, 9, v150
	v_and_or_b32 v148, v148, 8, v150
	v_mfma_f32_16x16x32_bf16 v[114:117], v[170:173], v[152:155], v[114:117]
	ds_read_b128 v[152:155], v178 offset:2048
	s_waitcnt lgkmcnt(0)
	v_mfma_f32_16x16x32_bf16 v[110:113], v[142:145], v[152:155], v[110:113]
	v_mfma_f32_16x16x32_bf16 v[106:109], v[162:165], v[152:155], v[106:109]
	v_mfma_f32_16x16x32_bf16 v[102:105], v[166:169], v[152:155], v[102:105]
	v_mfma_f32_16x16x32_bf16 v[98:101], v[170:173], v[152:155], v[98:101]
	ds_read_b128 v[152:155], v178 offset:4096
	s_waitcnt lgkmcnt(0)
	v_mfma_f32_16x16x32_bf16 v[94:97], v[142:145], v[152:155], v[94:97]
	v_mfma_f32_16x16x32_bf16 v[90:93], v[162:165], v[152:155], v[90:93]
	v_mfma_f32_16x16x32_bf16 v[86:89], v[166:169], v[152:155], v[86:89]
	v_mfma_f32_16x16x32_bf16 v[82:85], v[170:173], v[152:155], v[82:85]
	ds_read_b128 v[152:155], v178 offset:6144
	s_waitcnt lgkmcnt(0)
	v_mfma_f32_16x16x32_bf16 v[78:81], v[142:145], v[152:155], v[78:81]
	v_mfma_f32_16x16x32_bf16 v[74:77], v[162:165], v[152:155], v[74:77]
	v_mfma_f32_16x16x32_bf16 v[70:73], v[166:169], v[152:155], v[70:73]
	v_mfma_f32_16x16x32_bf16 v[66:69], v[170:173], v[152:155], v[66:69]
	ds_read_b128 v[152:155], v178 offset:8192
	ds_read_b128 v[174:177], v178 offset:10240
	s_waitcnt lgkmcnt(1)
	v_mfma_f32_16x16x32_bf16 v[62:65], v[142:145], v[152:155], v[62:65]
	v_mfma_f32_16x16x32_bf16 v[58:61], v[162:165], v[152:155], v[58:61]
	v_mfma_f32_16x16x32_bf16 v[54:57], v[166:169], v[152:155], v[54:57]
	v_mfma_f32_16x16x32_bf16 v[50:53], v[170:173], v[152:155], v[50:53]
	ds_read_b128 v[152:155], v178 offset:12288
	s_waitcnt lgkmcnt(1)
	v_mfma_f32_16x16x32_bf16 v[46:49], v[142:145], v[174:177], v[46:49]
	v_mfma_f32_16x16x32_bf16 v[42:45], v[162:165], v[174:177], v[42:45]
	v_mfma_f32_16x16x32_bf16 v[34:37], v[166:169], v[174:177], v[34:37]
	v_mfma_f32_16x16x32_bf16 v[30:33], v[170:173], v[174:177], v[30:33]
	ds_read_b128 v[174:177], v178 offset:14336
	s_waitcnt lgkmcnt(1)
	v_mfma_f32_16x16x32_bf16 v[178:181], v[142:145], v[152:155], v[26:29]
	s_nop 2
	v_lshl_add_u64 v[28:29], v[156:157], 0, s[12:13]
	v_add_u32_e32 v157, v184, v151
	v_lshl_add_u64 v[26:27], v[182:183], 0, s[12:13]
	ds_read_b128 v[182:185], v157
	ds_read_b128 v[186:189], v157 offset:2048
	ds_read_b128 v[190:193], v157 offset:4096
	ds_read_b128 v[194:197], v157 offset:6144
	v_add_u32_e32 v151, v198, v151
	v_mfma_f32_16x16x32_bf16 v[22:25], v[162:165], v[152:155], v[22:25]
	v_and_b32_e32 v156, 0xc0, v146
	v_lshl_or_b32 v149, v149, 2, v156
	s_mov_b32 s12, 0
	v_mfma_f32_16x16x32_bf16 v[18:21], v[166:169], v[152:155], v[18:21]
	v_mfma_f32_16x16x32_bf16 v[14:17], v[170:173], v[152:155], v[14:17]
	ds_read_b128 v[152:155], v151
	ds_read_b128 v[198:201], v151 offset:2048
	ds_read_b128 v[202:205], v151 offset:4096
	ds_read_b128 v[206:209], v151 offset:6144
	s_waitcnt lgkmcnt(8)
	v_mfma_f32_16x16x32_bf16 v[10:13], v[142:145], v[174:177], v[10:13]
	ds_read_b128 v[142:145], v151 offset:8192
	ds_read_b128 v[210:213], v151 offset:10240
	ds_read_b128 v[214:217], v151 offset:12288
	ds_read_b128 v[218:221], v151 offset:14336
	s_waitcnt lgkmcnt(0)
	s_barrier
; DEV unsigned cvt_pk_bf16(float lo, float hi) { const f32x2_t v = {lo, hi}; const bf16x2_t b = __builtin_convertvector(v, bf16x2_t); return __builtin_bit_cast(unsigned, b); }
; template <class Epi>
; DEV void gemm256_tile(const bf16_t* __restrict__ A, int lda, const bf16_t* __restrict__ Bt, int ldb, int K, unsigned char* lds, const Epi& epi) {
;     ...
;                 for (int mi = 0; mi < 4; ++mi)
; #pragma unroll
;                     for (int ni = 0; ni < 4; ++ni) acc[mh * 4 + mi][ni] = __builtin_amdgcn_mfma_f32_16x16x32_bf16(bfr[ni], af[mi], acc[mh * 4 + mi][ni], 0, 0, 0);
;             }
;         }
;     }
;     ...
;     __syncthreads();
;     if constexpr (Epi::STAGE) {
; #pragma unroll
;         for (int mi = 0; mi < 8; ++mi)
; #pragma unroll
;             for (int ni = 0; ni < 4; ++ni) {
;                 const int row = wr * 128 + mi * 16 + fr, col = wc * 64 + ni * 16 + fq * 4;
;                 const f32x4 v = epi.xform(row, col, acc[mi][ni]);
;                 uint2 w; w.x = cvt_pk_bf16(v[0], v[1]); w.y = cvt_pk_bf16(v[2], v[3]);
;                 *(uint2*)(lds + row * 512 + ((((col >> 3) ^ (row & 31)) << 4) | (((col >> 2) & 1) << 3))) = w;
;             }
;         __syncthreads();
	v_mfma_f32_16x16x32_bf16 v[2:5], v[166:169], v[174:177], v[2:5]
	v_mfma_f32_16x16x32_bf16 v[126:129], v[182:185], v[152:155], v[126:129]
	v_mfma_f32_16x16x32_bf16 v[114:117], v[194:197], v[152:155], v[114:117]
	v_mfma_f32_16x16x32_bf16 v[102:105], v[190:193], v[198:201], v[102:105]
	s_nop 5
	v_cvt_pk_bf16_f32 v126, v126, v127
	v_cvt_pk_bf16_f32 v127, v128, v129
	v_lshrrev_b32_e32 v128, 3, v149
	v_mfma_f32_16x16x32_bf16 v[34:37], v[190:193], v[210:213], v[34:37]
	v_cvt_pk_bf16_f32 v114, v114, v115
	v_cvt_pk_bf16_f32 v115, v116, v117
	v_or_b32_e32 v117, 16, v147
	v_mfma_f32_16x16x32_bf16 v[2:5], v[190:193], v[218:221], v[2:5]
	v_cvt_pk_bf16_f32 v102, v102, v103
	v_cvt_pk_bf16_f32 v103, v104, v105
	v_bitop3_b32 v104, v128, v117, 4 bitop3:0x36
	v_mfma_f32_16x16x32_bf16 v[38:41], v[170:173], v[174:177], v[38:41]
	v_lshl_add_u32 v104, v104, 4, v148
	v_cvt_pk_bf16_f32 v34, v34, v35
	v_cvt_pk_bf16_f32 v35, v36, v37
	v_mfma_f32_16x16x32_bf16 v[6:9], v[162:165], v[174:177], v[6:9]
	v_cvt_pk_bf16_f32 v2, v2, v3
	v_cvt_pk_bf16_f32 v3, v4, v5
	ds_write2st64_b64 v104, v[34:35], v[2:3] offset0:80 offset1:112
	v_mfma_f32_16x16x32_bf16 v[30:33], v[194:197], v[210:213], v[30:33]
	v_xor_b32_e32 v129, v128, v147
	v_bitop3_b32 v116, v128, v147, 6 bitop3:0x36
	v_lshl_or_b32 v129, v129, 4, v148
	v_mfma_f32_16x16x32_bf16 v[98:101], v[194:197], v[198:201], v[98:101]
	v_lshl_add_u32 v116, v116, 4, v148
	s_nop 2
	v_cvt_pk_bf16_f32 v36, v30, v31
	v_cvt_pk_bf16_f32 v37, v32, v33
	v_mfma_f32_16x16x32_bf16 v[122:125], v[186:189], v[152:155], v[122:125]
	v_mfma_f32_16x16x32_bf16 v[118:121], v[190:193], v[152:155], v[118:121]
	v_cvt_pk_bf16_f32 v98, v98, v99
	v_cvt_pk_bf16_f32 v99, v100, v101
	v_bitop3_b32 v100, v128, v117, 6 bitop3:0x36
	v_mfma_f32_16x16x32_bf16 v[110:113], v[182:185], v[198:201], v[110:113]
	s_nop 2
	v_cvt_pk_bf16_f32 v122, v122, v123
	v_cvt_pk_bf16_f32 v123, v124, v125
	v_bitop3_b32 v124, v128, v147, 2 bitop3:0x36
	v_mfma_f32_16x16x32_bf16 v[106:109], v[186:189], v[198:201], v[106:109]
	v_cvt_pk_bf16_f32 v118, v118, v119
	v_cvt_pk_bf16_f32 v119, v120, v121
	v_bitop3_b32 v120, v128, v147, 4 bitop3:0x36
	v_mfma_f32_16x16x32_bf16 v[2:5], v[194:197], v[218:221], v[38:41]
	v_cvt_pk_bf16_f32 v110, v110, v111
	v_cvt_pk_bf16_f32 v111, v112, v113
	v_bitop3_b32 v112, v128, v147, 16 bitop3:0x1e
	v_mfma_f32_16x16x32_bf16 v[94:97], v[182:185], v[202:205], v[94:97]
	v_cvt_pk_bf16_f32 v106, v106, v107
	v_cvt_pk_bf16_f32 v107, v108, v109
	v_bitop3_b32 v108, v128, v117, 2 bitop3:0x36
	v_mfma_f32_16x16x32_bf16 v[90:93], v[186:189], v[202:205], v[90:93]
	v_lshl_add_u32 v100, v100, 4, v148
	v_cvt_pk_bf16_f32 v2, v2, v3
	v_cvt_pk_bf16_f32 v3, v4, v5
	v_mfma_f32_16x16x32_bf16 v[86:89], v[190:193], v[202:205], v[86:89]
	v_lshl_add_u32 v124, v124, 4, v148
	v_lshl_add_u32 v120, v120, 4, v148
	v_lshl_or_b32 v112, v112, 4, v148
	v_mfma_f32_16x16x32_bf16 v[82:85], v[194:197], v[202:205], v[82:85]
	v_lshl_add_u32 v108, v108, 4, v148
	v_cvt_pk_bf16_f32 v94, v94, v95
	v_cvt_pk_bf16_f32 v95, v96, v97
	v_mfma_f32_16x16x32_bf16 v[78:81], v[182:185], v[206:209], v[78:81]
	v_cvt_pk_bf16_f32 v90, v90, v91
	v_cvt_pk_bf16_f32 v91, v92, v93
	v_cvt_pk_bf16_f32 v86, v86, v87
	v_mfma_f32_16x16x32_bf16 v[74:77], v[186:189], v[206:209], v[74:77]
	v_cvt_pk_bf16_f32 v87, v88, v89
	v_cvt_pk_bf16_f32 v82, v82, v83
	v_cvt_pk_bf16_f32 v83, v84, v85
	v_mfma_f32_16x16x32_bf16 v[70:73], v[190:193], v[206:209], v[70:73]
	v_cvt_pk_bf16_f32 v78, v78, v79
	v_cvt_pk_bf16_f32 v79, v80, v81
	s_nop 1
	v_cvt_pk_bf16_f32 v74, v74, v75
	v_mfma_f32_16x16x32_bf16 v[66:69], v[194:197], v[206:209], v[66:69]
	v_cvt_pk_bf16_f32 v75, v76, v77
	s_nop 0
	v_cvt_pk_bf16_f32 v70, v70, v71
	v_cvt_pk_bf16_f32 v71, v72, v73
	v_mfma_f32_16x16x32_bf16 v[62:65], v[182:185], v[142:145], v[62:65]
	ds_write2st64_b64 v100, v[36:37], v[2:3] offset0:80 offset1:112
	s_nop 1
	v_cvt_pk_bf16_f32 v66, v66, v67
	v_cvt_pk_bf16_f32 v67, v68, v69
	v_mfma_f32_16x16x32_bf16 v[58:61], v[186:189], v[142:145], v[58:61]
	v_and_b32_e32 v2, 0x1f0, v140
	s_nop 0
	v_cvt_pk_bf16_f32 v62, v62, v63
	v_cvt_pk_bf16_f32 v63, v64, v65
	v_mfma_f32_16x16x32_bf16 v[54:57], v[190:193], v[142:145], v[54:57]
	ds_write2st64_b64 v129, v[126:127], v[94:95] offset1:32
	s_nop 1
	v_cvt_pk_bf16_f32 v58, v58, v59
	v_cvt_pk_bf16_f32 v59, v60, v61
	v_mfma_f32_16x16x32_bf16 v[50:53], v[194:197], v[142:145], v[50:53]
	ds_write2st64_b64 v124, v[122:123], v[90:91] offset1:32
	s_nop 0
	v_cvt_pk_bf16_f32 v54, v54, v55
	v_cvt_pk_bf16_f32 v55, v56, v57
	v_mfma_f32_16x16x32_bf16 v[46:49], v[182:185], v[210:213], v[46:49]
	ds_write2st64_b64 v120, v[118:119], v[86:87] offset1:32
	s_nop 1
	v_cvt_pk_bf16_f32 v50, v50, v51
	v_cvt_pk_bf16_f32 v51, v52, v53
	v_mfma_f32_16x16x32_bf16 v[42:45], v[186:189], v[210:213], v[42:45]
	ds_write2st64_b64 v116, v[114:115], v[82:83] offset1:32
	s_nop 0
	v_cvt_pk_bf16_f32 v46, v46, v47
	v_cvt_pk_bf16_f32 v47, v48, v49
	v_mfma_f32_16x16x32_bf16 v[30:33], v[182:185], v[214:217], v[178:181]
	ds_write2st64_b64 v112, v[110:111], v[78:79] offset0:16 offset1:48
	s_nop 1
	v_cvt_pk_bf16_f32 v42, v42, v43
	v_cvt_pk_bf16_f32 v43, v44, v45
	v_mfma_f32_16x16x32_bf16 v[22:25], v[186:189], v[214:217], v[22:25]
	ds_write2st64_b64 v108, v[106:107], v[74:75] offset0:16 offset1:48
	s_nop 0
	v_cvt_pk_bf16_f32 v30, v30, v31
	v_cvt_pk_bf16_f32 v31, v32, v33
	v_mfma_f32_16x16x32_bf16 v[18:21], v[190:193], v[214:217], v[18:21]
	ds_write2st64_b64 v104, v[102:103], v[70:71] offset0:16 offset1:48
	s_nop 1
	v_cvt_pk_bf16_f32 v22, v22, v23
	v_cvt_pk_bf16_f32 v23, v24, v25
	v_mfma_f32_16x16x32_bf16 v[14:17], v[194:197], v[214:217], v[14:17]
	ds_write2st64_b64 v100, v[98:99], v[66:67] offset0:16 offset1:48
	s_nop 0
	v_cvt_pk_bf16_f32 v18, v18, v19
	v_cvt_pk_bf16_f32 v19, v20, v21
	v_mfma_f32_16x16x32_bf16 v[10:13], v[182:185], v[218:221], v[10:13]
	ds_write2st64_b64 v129, v[62:63], v[30:31] offset0:64 offset1:96
	s_nop 1
	v_cvt_pk_bf16_f32 v14, v14, v15
	v_cvt_pk_bf16_f32 v15, v16, v17
	v_mfma_f32_16x16x32_bf16 v[6:9], v[186:189], v[218:221], v[6:9]
	ds_write2st64_b64 v124, v[58:59], v[22:23] offset0:64 offset1:96
	s_nop 0
	v_cvt_pk_bf16_f32 v10, v10, v11
	v_cvt_pk_bf16_f32 v11, v12, v13
	ds_write2st64_b64 v120, v[54:55], v[18:19] offset0:64 offset1:96
	ds_write2st64_b64 v116, v[50:51], v[14:15] offset0:64 offset1:96
	s_nop 1
	v_cvt_pk_bf16_f32 v6, v6, v7
	v_cvt_pk_bf16_f32 v7, v8, v9
	ds_write2st64_b64 v112, v[46:47], v[10:11] offset0:80 offset1:112
	ds_write2st64_b64 v108, v[42:43], v[6:7] offset0:80 offset1:112
	s_waitcnt lgkmcnt(0)
	s_barrier
